# k16 plus: DMA queue drained at epilogue start, first-iteration counted waits skipped on non-first tiles (no stall on epilogue store acks) in 3 StaticOrder GEMMs
# baseline (speedup 1.0000x reference)
;     __device__ bool next(int i, Unit& u) const { if (i >= 2) return false; const int x = c & 7, j = c >> 3; u.pm = 32 * i + 4 * x + (j & 3); u.pn = j >> 2; return true; }
; #define PG8_STAGE(bufoff, gbase, voff) do { _Pragma("unroll") for (int _i = 0; _i < 2; ++_i) \
;         __builtin_amdgcn_global_load_lds((const unsigned*)((const char*)(gbase) + (voff)[_i]), (LAS unsigned*)(lds + (bufoff) + ldsw + _i * 8192), 16, 0, 0); } while (0)
; #define PG8_LDA(dst, b, h) do { _Pragma("unroll") for (int m = 0; m < 4; ++m) _Pragma("unroll") for (int k = 0; k < 2; ++k) dst[m][k] = *(const LAS bf16x8*)(lds + PG8_SA(b, h) + aoff + m * 2048 + k * 1024); } while (0)
; #define PG8_LDB(dst, b, h) do { _Pragma("unroll") for (int n = 0; n < 2; ++n) _Pragma("unroll") for (int k = 0; k < 2; ++k) dst[n][k] = *(const LAS bf16x8*)(lds + PG8_SB(b, h) + boff + n * 2048 + k * 1024); } while (0)
; #define PG8_WAIT_V(n) asm volatile("s_waitcnt vmcnt(" #n ")" ::: "memory")
; #define PG8_WAIT_L(n) asm volatile("s_waitcnt lgkmcnt(" #n ")" ::: "memory")
; #define PG8_BAR __builtin_amdgcn_s_barrier()
; template <class Epi, class Sched, bool ALIGN_EPI = true>
; __device__ __forceinline__ void gemm_phase(LAS unsigned char* lds, const Gemm g, const Sched& S, const Epi& E) {
;     ...
;         const bool has_next = S.next(ui + 1, nxt);
;         const char* nA = has_next ? (const char*)g.A + ((size_t)nxt.pm * BM * g.lda + (size_t)nxt.pn * g.a_pn_off) * 2 : cA; const char* nB = has_next ? (const char*)g.Bt + (size_t)nxt.pn * BM * g.ldb * 2 : cB;
;         for (int t = 0; t < nt; t += 2) {
;             const bool last = (t == nt - 2);
;             const char* a1 = cA + (size_t)(t + 1) * kstep;
;             const char* a2 = last ? nA : cA + (size_t)(t + 2) * kstep; const char* b2 = last ? nB : cB + (size_t)(t + 2) * kstep;
;             const char* a3 = a2 + kstep; const char* b3 = b2 + kstep;
;             PG8_LDB(B0, 0, 0); PG8_LDB(B1, 0, 1); PG8_SCHED; PG8_LDA(At, 0, 0); PG8_STAGE(PG8_SA(1, 1), a1 + hA, voffA);
;             PG8_WAIT_V(8); PG8_WAIT_L(0); PG8_BAR; PG8_MMA(0, 0, At, B0); PG8_MMA(0, 1, At, B1); PG8_BAR; PG8_SCHED;
;             PG8_LDA(At, 0, 1); PG8_STAGE(PG8_SB(0, 0), b2, voffB); PG8_STAGE(PG8_SB(0, 1), b2 + hB, voffB); PG8_STAGE(PG8_SA(0, 0), a2, voffA);
;             PG8_WAIT_V(8); PG8_WAIT_L(0); PG8_BAR; PG8_MMA(1, 0, At, B0); PG8_MMA(1, 1, At, B1); PG8_BAR; PG8_SCHED;
.LBB0_76:
	s_ashr_i32 s15, s14, 31
	s_lshl_b64 s[18:19], s[14:15], 20
	s_add_u32 s38, s46, s18
	s_addc_u32 s39, s47, s19
	s_and_b64 s[18:19], s[4:5], exec
	s_cselect_b32 s15, s39, s7
	s_cselect_b32 s17, s38, s6
	s_ashr_i32 s13, s12, 31
	s_lshl_b64 s[18:19], s[12:13], 20
	s_add_u32 s40, s53, s18
	s_addc_u32 s41, s58, s19
	s_and_b64 s[18:19], s[4:5], exec
	s_cselect_b32 s13, s41, s43
	s_cselect_b32 s18, s40, s42
	s_add_u32 s6, s6, 0x80080
	s_addc_u32 s7, s7, 0
	s_add_u32 s19, s42, 0x100
	s_addc_u32 s24, s43, 0
	s_mov_b32 s25, -2
	s_add_u32 s26, s6, 0xfff80080
	s_addc_u32 s27, s7, -1
	s_add_i32 s30, 0, 0x10000
	s_cmp_eq_u32 s25, 28
	s_cselect_b32 s45, s15, s27
	s_cselect_b32 s44, s17, s26
	s_cselect_b32 s43, s13, s24
	s_cselect_b32 s42, s18, s19
	s_add_i32 s31, 0, 0x14000
	v_add_u32_e32 v144, s30, v166
	v_add_u32_e32 v156, s31, v166
	ds_read_b128 v[132:135], v144
	ds_read_b128 v[136:139], v144 offset:1024
	ds_read_b128 v[140:143], v144 offset:2048
	ds_read_b128 v[144:147], v144 offset:3072
	ds_read_b128 v[170:173], v156
	ds_read_b128 v[174:177], v156 offset:1024
	ds_read_b128 v[178:181], v156 offset:2048
	ds_read_b128 v[182:185], v156 offset:3072
	v_lshl_add_u64 v[156:157], s[6:7], 0, v[152:153]
	s_add_i32 m0, s60, 0xc000
	ds_read_b128 v[186:189], v168
	ds_read_b128 v[190:193], v168 offset:1024
	ds_read_b128 v[194:197], v168 offset:2048
	ds_read_b128 v[204:207], v168 offset:3072
	ds_read_b128 v[208:211], v168 offset:4096
	ds_read_b128 v[212:215], v168 offset:5120
	ds_read_b128 v[216:219], v168 offset:6144
	ds_read_b128 v[220:223], v168 offset:7168
	global_load_lds_dwordx4 v[156:157], off
	v_lshl_add_u64 v[156:157], s[6:7], 0, v[154:155]
	s_add_i32 m0, s60, 0xe000
	s_nop 0
	global_load_lds_dwordx4 v[156:157], off
	s_cmp_gt_u32 s66, 1
	s_cbranch_scc1 .Lpw_77_0
	s_waitcnt vmcnt(8)
.Lpw_77_0:
	s_waitcnt lgkmcnt(0)
	s_barrier
	s_setprio 1
	s_waitcnt lgkmcnt(0)
	v_mfma_f32_16x16x32_bf16 v[128:131], v[132:135], v[186:189], 0
	v_mfma_f32_16x16x32_bf16 v[128:131], v[136:139], v[190:193], v[128:131]
	v_mfma_f32_16x16x32_bf16 v[124:127], v[140:143], v[186:189], 0
	v_mfma_f32_16x16x32_bf16 v[124:127], v[144:147], v[190:193], v[124:127]
	v_mfma_f32_16x16x32_bf16 v[116:119], v[132:135], v[194:197], 0
	v_mfma_f32_16x16x32_bf16 v[116:119], v[136:139], v[204:207], v[116:119]
	v_mfma_f32_16x16x32_bf16 v[112:115], v[140:143], v[194:197], 0
	v_mfma_f32_16x16x32_bf16 v[112:115], v[144:147], v[204:207], v[112:115]
	v_mfma_f32_16x16x32_bf16 v[104:107], v[132:135], v[208:211], 0
	v_mfma_f32_16x16x32_bf16 v[104:107], v[136:139], v[212:215], v[104:107]
	v_mfma_f32_16x16x32_bf16 v[96:99], v[140:143], v[208:211], 0
	v_mfma_f32_16x16x32_bf16 v[96:99], v[144:147], v[212:215], v[96:99]
	v_mfma_f32_16x16x32_bf16 v[88:91], v[132:135], v[216:219], 0
	v_mfma_f32_16x16x32_bf16 v[88:91], v[136:139], v[220:223], v[88:91]
	v_mfma_f32_16x16x32_bf16 v[80:83], v[140:143], v[216:219], 0
	v_mfma_f32_16x16x32_bf16 v[80:83], v[144:147], v[220:223], v[80:83]
	s_setprio 0
	s_setprio 1
	v_mfma_f32_16x16x32_bf16 v[120:123], v[170:173], v[186:189], 0
	v_mfma_f32_16x16x32_bf16 v[120:123], v[174:177], v[190:193], v[120:123]
	v_mfma_f32_16x16x32_bf16 v[108:111], v[178:181], v[186:189], 0
	v_mfma_f32_16x16x32_bf16 v[108:111], v[182:185], v[190:193], v[108:111]
	v_mfma_f32_16x16x32_bf16 v[100:103], v[170:173], v[194:197], 0
	v_mfma_f32_16x16x32_bf16 v[100:103], v[174:177], v[204:207], v[100:103]
	v_mfma_f32_16x16x32_bf16 v[92:95], v[178:181], v[194:197], 0
	v_mfma_f32_16x16x32_bf16 v[92:95], v[182:185], v[204:207], v[92:95]
	v_mfma_f32_16x16x32_bf16 v[84:87], v[170:173], v[208:211], 0
	v_mfma_f32_16x16x32_bf16 v[84:87], v[174:177], v[212:215], v[84:87]
	v_mfma_f32_16x16x32_bf16 v[76:79], v[178:181], v[208:211], 0
	v_mfma_f32_16x16x32_bf16 v[76:79], v[182:185], v[212:215], v[76:79]
	v_mfma_f32_16x16x32_bf16 v[72:75], v[170:173], v[216:219], 0
	v_mfma_f32_16x16x32_bf16 v[72:75], v[174:177], v[220:223], v[72:75]
	s_setprio 2
	s_barrier
	v_mfma_f32_16x16x32_bf16 v[68:71], v[178:181], v[216:219], 0
	v_mfma_f32_16x16x32_bf16 v[68:71], v[182:185], v[220:223], v[68:71]
	s_setprio 0
	s_add_i32 s26, s30, s59
	v_lshl_add_u64 v[156:157], s[42:43], 0, v[2:3]
	s_mov_b32 m0, s26
	ds_read_b128 v[186:189], v168 offset:16384
	ds_read_b128 v[190:193], v168 offset:17408
	ds_read_b128 v[194:197], v168 offset:18432
	ds_read_b128 v[204:207], v168 offset:19456
	ds_read_b128 v[208:211], v168 offset:20480
	ds_read_b128 v[212:215], v168 offset:21504
	ds_read_b128 v[216:219], v168 offset:22528
	ds_read_b128 v[220:223], v168 offset:23552
	global_load_lds_dwordx4 v[156:157], off
	s_add_i32 m0, s26, 0x2000
	s_add_u32 s26, s42, 0x80000
	v_lshl_add_u64 v[164:165], s[42:43], 0, v[0:1]
	s_addc_u32 s27, s43, 0
	s_add_i32 s30, s31, s59
	global_load_lds_dwordx4 v[164:165], off
	v_lshl_add_u64 v[224:225], s[26:27], 0, v[2:3]
	s_mov_b32 m0, s30
	v_lshl_add_u64 v[226:227], s[44:45], 0, v[148:149]
	global_load_lds_dwordx4 v[224:225], off
	v_lshl_add_u64 v[224:225], s[26:27], 0, v[0:1]
	s_add_i32 m0, s30, 0x2000
	s_nop 0
	global_load_lds_dwordx4 v[224:225], off
	v_lshl_add_u64 v[224:225], s[44:45], 0, v[150:151]
	s_mov_b32 m0, s60
	s_nop 0
	global_load_lds_dwordx4 v[224:225], off
	s_mov_b32 m0, s61
	s_nop 0
	global_load_lds_dwordx4 v[226:227], off
	s_cmp_gt_u32 s66, 1
	s_cbranch_scc1 .Lpw_77_1
	s_waitcnt vmcnt(8)
; #define PG8_STAGE(bufoff, gbase, voff) do { _Pragma("unroll") for (int _i = 0; _i < 2; ++_i) \
;         __builtin_amdgcn_global_load_lds((const unsigned*)((const char*)(gbase) + (voff)[_i]), (LAS unsigned*)(lds + (bufoff) + ldsw + _i * 8192), 16, 0, 0); } while (0)
; #define PG8_LDA(dst, b, h) do { _Pragma("unroll") for (int m = 0; m < 4; ++m) _Pragma("unroll") for (int k = 0; k < 2; ++k) dst[m][k] = *(const LAS bf16x8*)(lds + PG8_SA(b, h) + aoff + m * 2048 + k * 1024); } while (0)
; #define PG8_LDB(dst, b, h) do { _Pragma("unroll") for (int n = 0; n < 2; ++n) _Pragma("unroll") for (int k = 0; k < 2; ++k) dst[n][k] = *(const LAS bf16x8*)(lds + PG8_SB(b, h) + boff + n * 2048 + k * 1024); } while (0)
; #define PG8_MMA(ai, bj, At, Bt) do { __builtin_amdgcn_s_setprio(1); _Pragma("unroll") for (int m = 0; m < 4; ++m) _Pragma("unroll") for (int n = 0; n < 2; ++n) _Pragma("unroll") for (int k = 0; k < 2; ++k) \
;         acc[ai][bj][m][n] = __builtin_amdgcn_mfma_f32_16x16x32_bf16(Bt[n][k], At[m][k], acc[ai][bj][m][n], 0, 0, 0); __builtin_amdgcn_s_setprio(0); } while (0)
; #define PG8_WAIT_V(n) asm volatile("s_waitcnt vmcnt(" #n ")" ::: "memory")
; #define PG8_WAIT_L(n) asm volatile("s_waitcnt lgkmcnt(" #n ")" ::: "memory")
; #define PG8_BAR __builtin_amdgcn_s_barrier()
; #define PG8_SCHED __builtin_amdgcn_sched_barrier(0)
; template <class Epi, class Sched, bool ALIGN_EPI = true>
; __device__ __forceinline__ void gemm_phase(LAS unsigned char* lds, const Gemm g, const Sched& S, const Epi& E) {
;     ...
;             PG8_WAIT_V(8); PG8_WAIT_L(0); PG8_BAR; PG8_MMA(1, 0, At, B0); PG8_MMA(1, 1, At, B1); PG8_BAR; PG8_SCHED;
;             PG8_LDB(B0, 1, 0); PG8_LDB(B1, 1, 1); PG8_SCHED; PG8_LDA(At, 1, 0); PG8_STAGE(PG8_SA(0, 1), a2 + hA, voffA);
;             PG8_WAIT_V(8); PG8_WAIT_L(0); PG8_BAR; PG8_MMA(0, 0, At, B0); PG8_MMA(0, 1, At, B1); PG8_BAR; PG8_SCHED;
;             PG8_LDA(At, 1, 1); PG8_STAGE(PG8_SB(1, 0), b3, voffB); PG8_STAGE(PG8_SB(1, 1), b3 + hB, voffB); PG8_STAGE(PG8_SA(1, 0), a3, voffA);
;             PG8_WAIT_V(8); PG8_WAIT_L(0); PG8_BAR; PG8_MMA(1, 0, At, B0); PG8_MMA(1, 1, At, B1); PG8_BAR; PG8_SCHED;
.Lpw_77_1:
	s_waitcnt lgkmcnt(0)
	s_barrier
	s_setprio 1
	s_waitcnt lgkmcnt(0)
	v_mfma_f32_16x16x32_bf16 v[64:67], v[132:135], v[186:189], 0
	v_mfma_f32_16x16x32_bf16 v[64:67], v[136:139], v[190:193], v[64:67]
	v_mfma_f32_16x16x32_bf16 v[60:63], v[140:143], v[186:189], 0
	v_mfma_f32_16x16x32_bf16 v[60:63], v[144:147], v[190:193], v[60:63]
	v_mfma_f32_16x16x32_bf16 v[56:59], v[132:135], v[194:197], 0
	v_mfma_f32_16x16x32_bf16 v[56:59], v[136:139], v[204:207], v[56:59]
	v_mfma_f32_16x16x32_bf16 v[48:51], v[140:143], v[194:197], 0
	v_mfma_f32_16x16x32_bf16 v[48:51], v[144:147], v[204:207], v[48:51]
	v_mfma_f32_16x16x32_bf16 v[40:43], v[132:135], v[208:211], 0
	v_mfma_f32_16x16x32_bf16 v[40:43], v[136:139], v[212:215], v[40:43]
	v_mfma_f32_16x16x32_bf16 v[32:35], v[140:143], v[208:211], 0
	v_mfma_f32_16x16x32_bf16 v[32:35], v[144:147], v[212:215], v[32:35]
	v_mfma_f32_16x16x32_bf16 v[24:27], v[132:135], v[216:219], 0
	v_mfma_f32_16x16x32_bf16 v[24:27], v[136:139], v[220:223], v[24:27]
	v_mfma_f32_16x16x32_bf16 v[16:19], v[140:143], v[216:219], 0
	v_mfma_f32_16x16x32_bf16 v[16:19], v[144:147], v[220:223], v[16:19]
	s_setprio 0
	s_setprio 1
	v_mfma_f32_16x16x32_bf16 v[52:55], v[170:173], v[186:189], 0
	v_mfma_f32_16x16x32_bf16 v[52:55], v[174:177], v[190:193], v[52:55]
	v_mfma_f32_16x16x32_bf16 v[44:47], v[178:181], v[186:189], 0
	v_mfma_f32_16x16x32_bf16 v[44:47], v[182:185], v[190:193], v[44:47]
	v_mfma_f32_16x16x32_bf16 v[36:39], v[170:173], v[194:197], 0
	v_mfma_f32_16x16x32_bf16 v[36:39], v[174:177], v[204:207], v[36:39]
	v_mfma_f32_16x16x32_bf16 v[28:31], v[178:181], v[194:197], 0
	v_mfma_f32_16x16x32_bf16 v[28:31], v[182:185], v[204:207], v[28:31]
	v_mfma_f32_16x16x32_bf16 v[20:23], v[170:173], v[208:211], 0
	v_mfma_f32_16x16x32_bf16 v[20:23], v[174:177], v[212:215], v[20:23]
	v_mfma_f32_16x16x32_bf16 v[12:15], v[178:181], v[208:211], 0
	v_mfma_f32_16x16x32_bf16 v[12:15], v[182:185], v[212:215], v[12:15]
	v_mfma_f32_16x16x32_bf16 v[8:11], v[170:173], v[216:219], 0
	v_mfma_f32_16x16x32_bf16 v[8:11], v[174:177], v[220:223], v[8:11]
	s_setprio 2
	s_barrier
	v_mfma_f32_16x16x32_bf16 v[4:7], v[178:181], v[216:219], 0
	v_mfma_f32_16x16x32_bf16 v[4:7], v[182:185], v[220:223], v[4:7]
	s_setprio 0
	s_add_i32 s30, 0, 0x18000
	s_add_i32 s31, 0, 0x1c000
	v_add_u32_e32 v144, s30, v166
	v_add_u32_e32 v160, s31, v166
	ds_read_b128 v[132:135], v144
	ds_read_b128 v[136:139], v144 offset:1024
	ds_read_b128 v[140:143], v144 offset:2048
	ds_read_b128 v[144:147], v144 offset:3072
	ds_read_b128 v[170:173], v160
	ds_read_b128 v[174:177], v160 offset:1024
	ds_read_b128 v[178:181], v160 offset:2048
	ds_read_b128 v[182:185], v160 offset:3072
	s_add_u32 s26, s44, 0x80000
	s_addc_u32 s27, s45, 0
	s_mov_b32 m0, s62
	v_lshl_add_u64 v[228:229], s[26:27], 0, v[150:151]
	ds_read_b128 v[186:189], v168 offset:32768
	ds_read_b128 v[190:193], v168 offset:33792
	ds_read_b128 v[194:197], v168 offset:34816
	ds_read_b128 v[204:207], v168 offset:35840
	ds_read_b128 v[208:211], v168 offset:36864
	ds_read_b128 v[212:215], v168 offset:37888
	ds_read_b128 v[216:219], v168 offset:38912
	ds_read_b128 v[220:223], v168 offset:39936
	global_load_lds_dwordx4 v[228:229], off
	v_lshl_add_u64 v[228:229], s[26:27], 0, v[148:149]
	s_mov_b32 m0, s63
	s_nop 0
	global_load_lds_dwordx4 v[228:229], off
	s_waitcnt vmcnt(8)
	s_waitcnt lgkmcnt(0)
	s_barrier
	s_setprio 1
	s_waitcnt lgkmcnt(0)
	v_mfma_f32_16x16x32_bf16 v[128:131], v[132:135], v[186:189], v[128:131]
	v_mfma_f32_16x16x32_bf16 v[128:131], v[136:139], v[190:193], v[128:131]
	v_mfma_f32_16x16x32_bf16 v[124:127], v[140:143], v[186:189], v[124:127]
	v_mfma_f32_16x16x32_bf16 v[124:127], v[144:147], v[190:193], v[124:127]
	v_mfma_f32_16x16x32_bf16 v[116:119], v[132:135], v[194:197], v[116:119]
	v_mfma_f32_16x16x32_bf16 v[116:119], v[136:139], v[204:207], v[116:119]
	v_mfma_f32_16x16x32_bf16 v[112:115], v[140:143], v[194:197], v[112:115]
	v_mfma_f32_16x16x32_bf16 v[112:115], v[144:147], v[204:207], v[112:115]
	v_mfma_f32_16x16x32_bf16 v[104:107], v[132:135], v[208:211], v[104:107]
	v_mfma_f32_16x16x32_bf16 v[104:107], v[136:139], v[212:215], v[104:107]
	v_mfma_f32_16x16x32_bf16 v[96:99], v[140:143], v[208:211], v[96:99]
	v_mfma_f32_16x16x32_bf16 v[96:99], v[144:147], v[212:215], v[96:99]
	v_mfma_f32_16x16x32_bf16 v[88:91], v[132:135], v[216:219], v[88:91]
	v_mfma_f32_16x16x32_bf16 v[88:91], v[136:139], v[220:223], v[88:91]
	v_mfma_f32_16x16x32_bf16 v[80:83], v[140:143], v[216:219], v[80:83]
	v_mfma_f32_16x16x32_bf16 v[80:83], v[144:147], v[220:223], v[80:83]
	s_setprio 0
	s_setprio 1
	v_mfma_f32_16x16x32_bf16 v[120:123], v[170:173], v[186:189], v[120:123]
	v_mfma_f32_16x16x32_bf16 v[120:123], v[174:177], v[190:193], v[120:123]
	v_mfma_f32_16x16x32_bf16 v[108:111], v[178:181], v[186:189], v[108:111]
	v_mfma_f32_16x16x32_bf16 v[108:111], v[182:185], v[190:193], v[108:111]
	v_mfma_f32_16x16x32_bf16 v[100:103], v[170:173], v[194:197], v[100:103]
	v_mfma_f32_16x16x32_bf16 v[100:103], v[174:177], v[204:207], v[100:103]
	v_mfma_f32_16x16x32_bf16 v[92:95], v[178:181], v[194:197], v[92:95]
	v_mfma_f32_16x16x32_bf16 v[92:95], v[182:185], v[204:207], v[92:95]
	v_mfma_f32_16x16x32_bf16 v[84:87], v[170:173], v[208:211], v[84:87]
	v_mfma_f32_16x16x32_bf16 v[84:87], v[174:177], v[212:215], v[84:87]
	v_mfma_f32_16x16x32_bf16 v[76:79], v[178:181], v[208:211], v[76:79]
	v_mfma_f32_16x16x32_bf16 v[76:79], v[182:185], v[212:215], v[76:79]
	v_mfma_f32_16x16x32_bf16 v[72:75], v[170:173], v[216:219], v[72:75]
	v_mfma_f32_16x16x32_bf16 v[72:75], v[174:177], v[220:223], v[72:75]
	s_setprio 2
	s_barrier
; #define PG8_STAGE(bufoff, gbase, voff) do { _Pragma("unroll") for (int _i = 0; _i < 2; ++_i) \
;         __builtin_amdgcn_global_load_lds((const unsigned*)((const char*)(gbase) + (voff)[_i]), (LAS unsigned*)(lds + (bufoff) + ldsw + _i * 8192), 16, 0, 0); } while (0)
; #define PG8_LDA(dst, b, h) do { _Pragma("unroll") for (int m = 0; m < 4; ++m) _Pragma("unroll") for (int k = 0; k < 2; ++k) dst[m][k] = *(const LAS bf16x8*)(lds + PG8_SA(b, h) + aoff + m * 2048 + k * 1024); } while (0)
; #define PG8_MMA(ai, bj, At, Bt) do { __builtin_amdgcn_s_setprio(1); _Pragma("unroll") for (int m = 0; m < 4; ++m) _Pragma("unroll") for (int n = 0; n < 2; ++n) _Pragma("unroll") for (int k = 0; k < 2; ++k) \
;         acc[ai][bj][m][n] = __builtin_amdgcn_mfma_f32_16x16x32_bf16(Bt[n][k], At[m][k], acc[ai][bj][m][n], 0, 0, 0); __builtin_amdgcn_s_setprio(0); } while (0)
; #define PG8_WAIT_V(n) asm volatile("s_waitcnt vmcnt(" #n ")" ::: "memory")
; #define PG8_WAIT_L(n) asm volatile("s_waitcnt lgkmcnt(" #n ")" ::: "memory")
; #define PG8_BAR __builtin_amdgcn_s_barrier()
; #define PG8_SCHED __builtin_amdgcn_sched_barrier(0)
; template <class Epi, class Sched, bool ALIGN_EPI = true>
; __device__ __forceinline__ void gemm_phase(LAS unsigned char* lds, const Gemm g, const Sched& S, const Epi& E) {
;     ...
;             PG8_LDA(At, 1, 1); PG8_STAGE(PG8_SB(1, 0), b3, voffB); PG8_STAGE(PG8_SB(1, 1), b3 + hB, voffB); PG8_STAGE(PG8_SA(1, 0), a3, voffA);
;             PG8_WAIT_V(8); PG8_WAIT_L(0); PG8_BAR; PG8_MMA(1, 0, At, B0); PG8_MMA(1, 1, At, B1); PG8_BAR; PG8_SCHED;
;         }
	v_mfma_f32_16x16x32_bf16 v[68:71], v[178:181], v[216:219], v[68:71]
	v_mfma_f32_16x16x32_bf16 v[68:71], v[182:185], v[220:223], v[68:71]
	s_setprio 0
	s_add_i32 s26, s30, s59
	v_lshl_add_u64 v[156:157], v[156:157], 0, s[86:87]
	s_mov_b32 m0, s26
	ds_read_b128 v[186:189], v168 offset:49152
	ds_read_b128 v[190:193], v168 offset:50176
	ds_read_b128 v[194:197], v168 offset:51200
	ds_read_b128 v[204:207], v168 offset:52224
	ds_read_b128 v[208:211], v168 offset:53248
	ds_read_b128 v[212:215], v168 offset:54272
	ds_read_b128 v[216:219], v168 offset:55296
	ds_read_b128 v[220:223], v168 offset:56320
	global_load_lds_dwordx4 v[156:157], off
	s_add_i32 m0, s26, 0x2000
	s_add_u32 s26, s42, 0x80080
	v_lshl_add_u64 v[156:157], v[164:165], 0, s[86:87]
	s_addc_u32 s27, s43, 0
	s_add_i32 s30, s31, s59
	global_load_lds_dwordx4 v[156:157], off
	v_lshl_add_u64 v[156:157], s[26:27], 0, v[2:3]
	s_mov_b32 m0, s30
	s_nop 0
	global_load_lds_dwordx4 v[156:157], off
	v_lshl_add_u64 v[156:157], s[26:27], 0, v[0:1]
	s_add_i32 m0, s30, 0x2000
	s_nop 0
	global_load_lds_dwordx4 v[156:157], off
	v_lshl_add_u64 v[156:157], v[224:225], 0, s[86:87]
	s_mov_b32 m0, s64
	s_nop 0
	global_load_lds_dwordx4 v[156:157], off
	v_lshl_add_u64 v[156:157], v[226:227], 0, s[86:87]
	s_mov_b32 m0, s65
	s_nop 0
	global_load_lds_dwordx4 v[156:157], off
	s_waitcnt vmcnt(8)
	s_waitcnt lgkmcnt(0)
	s_barrier
	s_setprio 1
	s_waitcnt lgkmcnt(0)
	v_mfma_f32_16x16x32_bf16 v[64:67], v[132:135], v[186:189], v[64:67]
	v_mfma_f32_16x16x32_bf16 v[64:67], v[136:139], v[190:193], v[64:67]
	v_mfma_f32_16x16x32_bf16 v[60:63], v[140:143], v[186:189], v[60:63]
	v_mfma_f32_16x16x32_bf16 v[60:63], v[144:147], v[190:193], v[60:63]
	v_mfma_f32_16x16x32_bf16 v[56:59], v[132:135], v[194:197], v[56:59]
	v_mfma_f32_16x16x32_bf16 v[56:59], v[136:139], v[204:207], v[56:59]
	v_mfma_f32_16x16x32_bf16 v[48:51], v[140:143], v[194:197], v[48:51]
	v_mfma_f32_16x16x32_bf16 v[48:51], v[144:147], v[204:207], v[48:51]
	v_mfma_f32_16x16x32_bf16 v[40:43], v[132:135], v[208:211], v[40:43]
	v_mfma_f32_16x16x32_bf16 v[40:43], v[136:139], v[212:215], v[40:43]
	v_mfma_f32_16x16x32_bf16 v[32:35], v[140:143], v[208:211], v[32:35]
	v_mfma_f32_16x16x32_bf16 v[32:35], v[144:147], v[212:215], v[32:35]
	v_mfma_f32_16x16x32_bf16 v[24:27], v[132:135], v[216:219], v[24:27]
	v_mfma_f32_16x16x32_bf16 v[24:27], v[136:139], v[220:223], v[24:27]
	v_mfma_f32_16x16x32_bf16 v[16:19], v[140:143], v[216:219], v[16:19]
	v_mfma_f32_16x16x32_bf16 v[16:19], v[144:147], v[220:223], v[16:19]
	s_setprio 0
	s_setprio 1
	v_mfma_f32_16x16x32_bf16 v[52:55], v[170:173], v[186:189], v[52:55]
	v_mfma_f32_16x16x32_bf16 v[52:55], v[174:177], v[190:193], v[52:55]
	v_mfma_f32_16x16x32_bf16 v[44:47], v[178:181], v[186:189], v[44:47]
	v_mfma_f32_16x16x32_bf16 v[44:47], v[182:185], v[190:193], v[44:47]
	v_mfma_f32_16x16x32_bf16 v[36:39], v[170:173], v[194:197], v[36:39]
	v_mfma_f32_16x16x32_bf16 v[36:39], v[174:177], v[204:207], v[36:39]
	v_mfma_f32_16x16x32_bf16 v[28:31], v[178:181], v[194:197], v[28:31]
	v_mfma_f32_16x16x32_bf16 v[28:31], v[182:185], v[204:207], v[28:31]
	v_mfma_f32_16x16x32_bf16 v[20:23], v[170:173], v[208:211], v[20:23]
	v_mfma_f32_16x16x32_bf16 v[20:23], v[174:177], v[212:215], v[20:23]
	v_mfma_f32_16x16x32_bf16 v[12:15], v[178:181], v[208:211], v[12:15]
	v_mfma_f32_16x16x32_bf16 v[12:15], v[182:185], v[212:215], v[12:15]
	v_mfma_f32_16x16x32_bf16 v[8:11], v[170:173], v[216:219], v[8:11]
	v_mfma_f32_16x16x32_bf16 v[8:11], v[174:177], v[220:223], v[8:11]
	s_setprio 2
	s_barrier
	v_mfma_f32_16x16x32_bf16 v[4:7], v[178:181], v[216:219], v[4:7]
	v_mfma_f32_16x16x32_bf16 v[4:7], v[182:185], v[220:223], v[4:7]
	s_setprio 0
	s_add_i32 s25, s25, 2
	s_add_u32 s6, s6, 0x100
	s_addc_u32 s7, s7, 0
	s_add_u32 s19, s19, 0x100
	s_addc_u32 s24, s24, 0
	s_cmp_gt_u32 s25, 29
	s_cbranch_scc1 .Lpeel_exit_77

; #define PG8_BAR __builtin_amdgcn_s_barrier()
;     __device__ __forceinline__ void operator()(f32x4 (&acc)[2][2][4][2], const Unit& u, int wr, int wc, int fr, int fq, int wid, int lane) const {
;         const int row0 = u.pm * BM + wr * 64 + fr; const int bcol0 = u.pn * BM + wc * 32 + 8 * fq; const int col0 = ocol_off + bcol0;
;         f32x4 bv[2][2], sv[2][2];
; #pragma unroll
;         for (int bj = 0; bj < 2; ++bj)
; #pragma unroll
;             for (int n = 0; n < 2; ++n) { bv[bj][n] = bias ? *(const f32x4*)(bias + bcol0 + bj * HALF + 4 * n) : (f32x4){0.f, 0.f, 0.f, 0.f};
;                                           sv[bj][n] = scale ? *(const f32x4*)(scale + bcol0 + bj * HALF + 4 * n) : (f32x4){1.f, 1.f, 1.f, 1.f}; }
; template <class Epi, class Sched, bool ALIGN_EPI = true>
; __device__ __forceinline__ void gemm_phase(LAS unsigned char* lds, const Gemm g, const Sched& S, const Epi& E) {
;     ...
;         if constexpr (ALIGN_EPI) { if (wr == 0) PG8_BAR; }
;         E(acc, cur, wr, wc, fr, fq, wid, lane);
.LBB0_80:
	s_waitcnt vmcnt(0)
	v_lshl_or_b32 v164, s16, 8, v167
	v_readlane_b32 s16, v251, 52
	v_readlane_b32 s17, v251, 53
	v_ashrrev_i32_e32 v165, 31, v164
	v_lshl_add_u64 v[156:157], v[164:165], 2, s[8:9]
	v_cndmask_b32_e64 v133, 0, 1, s[16:17]
	v_mov_b32_e32 v132, 0
	v_cmp_ne_u32_e64 s[6:7], 1, v133
	s_andn2_b64 vcc, exec, s[16:17]
	v_mov_b32_e32 v136, 0
	v_mov_b32_e32 v137, 0
	v_mov_b32_e32 v138, 0
	v_mov_b32_e32 v139, 0
	s_cbranch_vccnz .LBB0_82
	global_load_dwordx4 v[136:139], v[156:157], off

;     __device__ bool next(int i, Unit& u) const { if (i >= 2) return false; const int x = c & 7, j = c >> 3; u.pm = 32 * i + 4 * x + (j & 3); u.pn = j >> 2; return true; }
; #define PG8_STAGE(bufoff, gbase, voff) do { _Pragma("unroll") for (int _i = 0; _i < 2; ++_i) \
;         __builtin_amdgcn_global_load_lds((const unsigned*)((const char*)(gbase) + (voff)[_i]), (LAS unsigned*)(lds + (bufoff) + ldsw + _i * 8192), 16, 0, 0); } while (0)
; #define PG8_LDA(dst, b, h) do { _Pragma("unroll") for (int m = 0; m < 4; ++m) _Pragma("unroll") for (int k = 0; k < 2; ++k) dst[m][k] = *(const LAS bf16x8*)(lds + PG8_SA(b, h) + aoff + m * 2048 + k * 1024); } while (0)
; #define PG8_LDB(dst, b, h) do { _Pragma("unroll") for (int n = 0; n < 2; ++n) _Pragma("unroll") for (int k = 0; k < 2; ++k) dst[n][k] = *(const LAS bf16x8*)(lds + PG8_SB(b, h) + boff + n * 2048 + k * 1024); } while (0)
; #define PG8_WAIT_V(n) asm volatile("s_waitcnt vmcnt(" #n ")" ::: "memory")
; #define PG8_WAIT_L(n) asm volatile("s_waitcnt lgkmcnt(" #n ")" ::: "memory")
; #define PG8_BAR __builtin_amdgcn_s_barrier()
; template <class Epi, class Sched, bool ALIGN_EPI = true>
; __device__ __forceinline__ void gemm_phase(LAS unsigned char* lds, const Gemm g, const Sched& S, const Epi& E) {
;     ...
;         const bool has_next = S.next(ui + 1, nxt);
;         const char* nA = has_next ? (const char*)g.A + ((size_t)nxt.pm * BM * g.lda + (size_t)nxt.pn * g.a_pn_off) * 2 : cA; const char* nB = has_next ? (const char*)g.Bt + (size_t)nxt.pn * BM * g.ldb * 2 : cB;
;         for (int t = 0; t < nt; t += 2) {
;             const bool last = (t == nt - 2);
;             const char* a1 = cA + (size_t)(t + 1) * kstep;
;             const char* a2 = last ? nA : cA + (size_t)(t + 2) * kstep; const char* b2 = last ? nB : cB + (size_t)(t + 2) * kstep;
;             const char* a3 = a2 + kstep; const char* b3 = b2 + kstep;
;             PG8_LDB(B0, 0, 0); PG8_LDB(B1, 0, 1); PG8_SCHED; PG8_LDA(At, 0, 0); PG8_STAGE(PG8_SA(1, 1), a1 + hA, voffA);
;             PG8_WAIT_V(8); PG8_WAIT_L(0); PG8_BAR; PG8_MMA(0, 0, At, B0); PG8_MMA(0, 1, At, B1); PG8_BAR; PG8_SCHED;
;             PG8_LDA(At, 0, 1); PG8_STAGE(PG8_SB(0, 0), b2, voffB); PG8_STAGE(PG8_SB(0, 1), b2 + hB, voffB); PG8_STAGE(PG8_SA(0, 0), a2, voffA);
;             PG8_WAIT_V(8); PG8_WAIT_L(0); PG8_BAR; PG8_MMA(1, 0, At, B0); PG8_MMA(1, 1, At, B1); PG8_BAR; PG8_SCHED;
.LBB0_217:
	s_ashr_i32 s11, s10, 31
	s_lshl_b64 s[12:13], s[10:11], 20
	s_add_u32 s12, s46, s12
	s_addc_u32 s13, s47, s13
	s_and_b64 s[14:15], s[4:5], exec
	s_cselect_b32 s11, s13, s39
	s_cselect_b32 s18, s12, s38
	s_ashr_i32 s9, s8, 31
	s_lshl_b64 s[14:15], s[8:9], 20
	s_add_u32 s14, s44, s14
	s_addc_u32 s15, s45, s15
	s_and_b64 s[24:25], s[4:5], exec
	s_cselect_b32 s9, s15, s41
	s_cselect_b32 s19, s14, s40
	s_add_u32 s38, s38, 0x80080
	s_addc_u32 s39, s39, 0
	s_add_u32 s24, s40, 0x100
	s_addc_u32 s25, s41, 0
	s_mov_b32 s26, -2
	s_add_u32 s27, s38, 0xfff80080
	s_addc_u32 s30, s39, -1
	s_add_i32 s31, 0, 0x10000
	s_cmp_eq_u32 s26, 28
	s_cselect_b32 s43, s11, s30
	s_cselect_b32 s42, s18, s27
	v_add_u32_e32 v156, s31, v145
	s_cselect_b32 s41, s9, s25
	s_cselect_b32 s40, s19, s24
	s_add_i32 s27, 0, 0x14000
	ds_read_b128 v[140:143], v156
	ds_read_b128 v[148:151], v156 offset:1024
	ds_read_b128 v[152:155], v156 offset:2048
	ds_read_b128 v[164:167], v156 offset:3072
	v_add_u32_e32 v156, s27, v145
	ds_read_b128 v[168:171], v156
	ds_read_b128 v[172:175], v156 offset:1024
	ds_read_b128 v[176:179], v156 offset:2048
	ds_read_b128 v[180:183], v156 offset:3072
	v_lshl_add_u64 v[156:157], s[38:39], 0, v[136:137]
	s_add_i32 m0, s58, 0xc000
	ds_read_b128 v[184:187], v147
	ds_read_b128 v[188:191], v147 offset:1024
	ds_read_b128 v[192:195], v147 offset:2048
	ds_read_b128 v[204:207], v147 offset:3072
	ds_read_b128 v[208:211], v147 offset:4096
	ds_read_b128 v[212:215], v147 offset:5120
	ds_read_b128 v[216:219], v147 offset:6144
	ds_read_b128 v[220:223], v147 offset:7168
	global_load_lds_dwordx4 v[156:157], off
	v_lshl_add_u64 v[156:157], s[38:39], 0, v[138:139]
	s_add_i32 m0, s58, 0xe000
	s_nop 0
	global_load_lds_dwordx4 v[156:157], off
	s_cmp_gt_u32 s64, 1
	s_cbranch_scc1 .Lpw_218_0
	s_waitcnt vmcnt(8)
.Lpw_218_0:
	s_waitcnt lgkmcnt(0)
	s_barrier
	s_setprio 1
	s_waitcnt lgkmcnt(0)
	v_mfma_f32_16x16x32_bf16 v[128:131], v[140:143], v[184:187], 0
	v_mfma_f32_16x16x32_bf16 v[128:131], v[148:151], v[188:191], v[128:131]
	v_mfma_f32_16x16x32_bf16 v[124:127], v[152:155], v[184:187], 0
	v_mfma_f32_16x16x32_bf16 v[124:127], v[164:167], v[188:191], v[124:127]
	v_mfma_f32_16x16x32_bf16 v[120:123], v[140:143], v[192:195], 0
	v_mfma_f32_16x16x32_bf16 v[120:123], v[148:151], v[204:207], v[120:123]
	v_mfma_f32_16x16x32_bf16 v[112:115], v[152:155], v[192:195], 0
	v_mfma_f32_16x16x32_bf16 v[112:115], v[164:167], v[204:207], v[112:115]
	v_mfma_f32_16x16x32_bf16 v[104:107], v[140:143], v[208:211], 0
	v_mfma_f32_16x16x32_bf16 v[104:107], v[148:151], v[212:215], v[104:107]
	v_mfma_f32_16x16x32_bf16 v[96:99], v[152:155], v[208:211], 0
	v_mfma_f32_16x16x32_bf16 v[96:99], v[164:167], v[212:215], v[96:99]
	v_mfma_f32_16x16x32_bf16 v[88:91], v[140:143], v[216:219], 0
	v_mfma_f32_16x16x32_bf16 v[88:91], v[148:151], v[220:223], v[88:91]
	v_mfma_f32_16x16x32_bf16 v[80:83], v[152:155], v[216:219], 0
	v_mfma_f32_16x16x32_bf16 v[80:83], v[164:167], v[220:223], v[80:83]
	s_setprio 0
	s_setprio 1
	v_mfma_f32_16x16x32_bf16 v[116:119], v[168:171], v[184:187], 0
	v_mfma_f32_16x16x32_bf16 v[116:119], v[172:175], v[188:191], v[116:119]
	v_mfma_f32_16x16x32_bf16 v[108:111], v[176:179], v[184:187], 0
	v_mfma_f32_16x16x32_bf16 v[108:111], v[180:183], v[188:191], v[108:111]
	v_mfma_f32_16x16x32_bf16 v[100:103], v[168:171], v[192:195], 0
	v_mfma_f32_16x16x32_bf16 v[100:103], v[172:175], v[204:207], v[100:103]
	v_mfma_f32_16x16x32_bf16 v[92:95], v[176:179], v[192:195], 0
	v_mfma_f32_16x16x32_bf16 v[92:95], v[180:183], v[204:207], v[92:95]
	v_mfma_f32_16x16x32_bf16 v[84:87], v[168:171], v[208:211], 0
	v_mfma_f32_16x16x32_bf16 v[84:87], v[172:175], v[212:215], v[84:87]
	v_mfma_f32_16x16x32_bf16 v[76:79], v[176:179], v[208:211], 0
	v_mfma_f32_16x16x32_bf16 v[76:79], v[180:183], v[212:215], v[76:79]
	v_mfma_f32_16x16x32_bf16 v[72:75], v[168:171], v[216:219], 0
	v_mfma_f32_16x16x32_bf16 v[72:75], v[172:175], v[220:223], v[72:75]
	s_setprio 2
	s_barrier
	v_mfma_f32_16x16x32_bf16 v[68:71], v[176:179], v[216:219], 0
	v_mfma_f32_16x16x32_bf16 v[68:71], v[180:183], v[220:223], v[68:71]
	s_setprio 0
	s_add_i32 s30, s31, s53
	v_lshl_add_u64 v[156:157], s[40:41], 0, v[2:3]
	s_mov_b32 m0, s30
	ds_read_b128 v[184:187], v147 offset:16384
	ds_read_b128 v[188:191], v147 offset:17408
	ds_read_b128 v[192:195], v147 offset:18432
	ds_read_b128 v[204:207], v147 offset:19456
	ds_read_b128 v[208:211], v147 offset:20480
	ds_read_b128 v[212:215], v147 offset:21504
	ds_read_b128 v[216:219], v147 offset:22528
	ds_read_b128 v[220:223], v147 offset:23552
	global_load_lds_dwordx4 v[156:157], off
	s_add_i32 m0, s30, 0x2000
	s_add_u32 s30, s40, 0x80000
	v_lshl_add_u64 v[196:197], s[40:41], 0, v[0:1]
	s_addc_u32 s31, s41, 0
	s_add_i32 s27, s27, s53
	global_load_lds_dwordx4 v[196:197], off
	v_lshl_add_u64 v[224:225], s[30:31], 0, v[2:3]
	s_mov_b32 m0, s27
	v_lshl_add_u64 v[226:227], s[42:43], 0, v[132:133]
	global_load_lds_dwordx4 v[224:225], off
	v_lshl_add_u64 v[224:225], s[30:31], 0, v[0:1]
	s_add_i32 m0, s27, 0x2000
	s_nop 0
	global_load_lds_dwordx4 v[224:225], off
	v_lshl_add_u64 v[224:225], s[42:43], 0, v[134:135]
	s_mov_b32 m0, s58
	s_nop 0
	global_load_lds_dwordx4 v[224:225], off
	s_mov_b32 m0, s59
	s_nop 0
	global_load_lds_dwordx4 v[226:227], off
	s_cmp_gt_u32 s64, 1
	s_cbranch_scc1 .Lpw_218_1
	s_waitcnt vmcnt(8)
; #define PG8_STAGE(bufoff, gbase, voff) do { _Pragma("unroll") for (int _i = 0; _i < 2; ++_i) \
;         __builtin_amdgcn_global_load_lds((const unsigned*)((const char*)(gbase) + (voff)[_i]), (LAS unsigned*)(lds + (bufoff) + ldsw + _i * 8192), 16, 0, 0); } while (0)
; #define PG8_LDA(dst, b, h) do { _Pragma("unroll") for (int m = 0; m < 4; ++m) _Pragma("unroll") for (int k = 0; k < 2; ++k) dst[m][k] = *(const LAS bf16x8*)(lds + PG8_SA(b, h) + aoff + m * 2048 + k * 1024); } while (0)
; #define PG8_LDB(dst, b, h) do { _Pragma("unroll") for (int n = 0; n < 2; ++n) _Pragma("unroll") for (int k = 0; k < 2; ++k) dst[n][k] = *(const LAS bf16x8*)(lds + PG8_SB(b, h) + boff + n * 2048 + k * 1024); } while (0)
; #define PG8_MMA(ai, bj, At, Bt) do { __builtin_amdgcn_s_setprio(1); _Pragma("unroll") for (int m = 0; m < 4; ++m) _Pragma("unroll") for (int n = 0; n < 2; ++n) _Pragma("unroll") for (int k = 0; k < 2; ++k) \
;         acc[ai][bj][m][n] = __builtin_amdgcn_mfma_f32_16x16x32_bf16(Bt[n][k], At[m][k], acc[ai][bj][m][n], 0, 0, 0); __builtin_amdgcn_s_setprio(0); } while (0)
; #define PG8_WAIT_V(n) asm volatile("s_waitcnt vmcnt(" #n ")" ::: "memory")
; #define PG8_WAIT_L(n) asm volatile("s_waitcnt lgkmcnt(" #n ")" ::: "memory")
; #define PG8_BAR __builtin_amdgcn_s_barrier()
; #define PG8_SCHED __builtin_amdgcn_sched_barrier(0)
; template <class Epi, class Sched, bool ALIGN_EPI = true>
; __device__ __forceinline__ void gemm_phase(LAS unsigned char* lds, const Gemm g, const Sched& S, const Epi& E) {
;     ...
;             PG8_WAIT_V(8); PG8_WAIT_L(0); PG8_BAR; PG8_MMA(1, 0, At, B0); PG8_MMA(1, 1, At, B1); PG8_BAR; PG8_SCHED;
;             PG8_LDB(B0, 1, 0); PG8_LDB(B1, 1, 1); PG8_SCHED; PG8_LDA(At, 1, 0); PG8_STAGE(PG8_SA(0, 1), a2 + hA, voffA);
;             PG8_WAIT_V(8); PG8_WAIT_L(0); PG8_BAR; PG8_MMA(0, 0, At, B0); PG8_MMA(0, 1, At, B1); PG8_BAR; PG8_SCHED;
;             PG8_LDA(At, 1, 1); PG8_STAGE(PG8_SB(1, 0), b3, voffB); PG8_STAGE(PG8_SB(1, 1), b3 + hB, voffB); PG8_STAGE(PG8_SA(1, 0), a3, voffA);
;             PG8_WAIT_V(8); PG8_WAIT_L(0); PG8_BAR; PG8_MMA(1, 0, At, B0); PG8_MMA(1, 1, At, B1); PG8_BAR; PG8_SCHED;
.Lpw_218_1:
	s_waitcnt lgkmcnt(0)
	s_barrier
	s_setprio 1
	s_waitcnt lgkmcnt(0)
	v_mfma_f32_16x16x32_bf16 v[64:67], v[140:143], v[184:187], 0
	v_mfma_f32_16x16x32_bf16 v[64:67], v[148:151], v[188:191], v[64:67]
	v_mfma_f32_16x16x32_bf16 v[60:63], v[152:155], v[184:187], 0
	v_mfma_f32_16x16x32_bf16 v[60:63], v[164:167], v[188:191], v[60:63]
	v_mfma_f32_16x16x32_bf16 v[56:59], v[140:143], v[192:195], 0
	v_mfma_f32_16x16x32_bf16 v[56:59], v[148:151], v[204:207], v[56:59]
	v_mfma_f32_16x16x32_bf16 v[48:51], v[152:155], v[192:195], 0
	v_mfma_f32_16x16x32_bf16 v[48:51], v[164:167], v[204:207], v[48:51]
	v_mfma_f32_16x16x32_bf16 v[40:43], v[140:143], v[208:211], 0
	v_mfma_f32_16x16x32_bf16 v[40:43], v[148:151], v[212:215], v[40:43]
	v_mfma_f32_16x16x32_bf16 v[32:35], v[152:155], v[208:211], 0
	v_mfma_f32_16x16x32_bf16 v[32:35], v[164:167], v[212:215], v[32:35]
	v_mfma_f32_16x16x32_bf16 v[24:27], v[140:143], v[216:219], 0
	v_mfma_f32_16x16x32_bf16 v[24:27], v[148:151], v[220:223], v[24:27]
	v_mfma_f32_16x16x32_bf16 v[16:19], v[152:155], v[216:219], 0
	v_mfma_f32_16x16x32_bf16 v[16:19], v[164:167], v[220:223], v[16:19]
	s_setprio 0
	s_setprio 1
	v_mfma_f32_16x16x32_bf16 v[52:55], v[168:171], v[184:187], 0
	v_mfma_f32_16x16x32_bf16 v[52:55], v[172:175], v[188:191], v[52:55]
	v_mfma_f32_16x16x32_bf16 v[44:47], v[176:179], v[184:187], 0
	v_mfma_f32_16x16x32_bf16 v[44:47], v[180:183], v[188:191], v[44:47]
	v_mfma_f32_16x16x32_bf16 v[36:39], v[168:171], v[192:195], 0
	v_mfma_f32_16x16x32_bf16 v[36:39], v[172:175], v[204:207], v[36:39]
	v_mfma_f32_16x16x32_bf16 v[28:31], v[176:179], v[192:195], 0
	v_mfma_f32_16x16x32_bf16 v[28:31], v[180:183], v[204:207], v[28:31]
	v_mfma_f32_16x16x32_bf16 v[20:23], v[168:171], v[208:211], 0
	v_mfma_f32_16x16x32_bf16 v[20:23], v[172:175], v[212:215], v[20:23]
	v_mfma_f32_16x16x32_bf16 v[12:15], v[176:179], v[208:211], 0
	v_mfma_f32_16x16x32_bf16 v[12:15], v[180:183], v[212:215], v[12:15]
	v_mfma_f32_16x16x32_bf16 v[8:11], v[168:171], v[216:219], 0
	v_mfma_f32_16x16x32_bf16 v[8:11], v[172:175], v[220:223], v[8:11]
	s_setprio 2
	s_barrier
	v_mfma_f32_16x16x32_bf16 v[4:7], v[176:179], v[216:219], 0
	v_mfma_f32_16x16x32_bf16 v[4:7], v[180:183], v[220:223], v[4:7]
	s_setprio 0
	s_add_i32 s27, 0, 0x18000
	v_add_u32_e32 v158, s27, v145
	s_add_i32 s65, 0, 0x1c000
	ds_read_b128 v[140:143], v158
	ds_read_b128 v[148:151], v158 offset:1024
	ds_read_b128 v[152:155], v158 offset:2048
	ds_read_b128 v[164:167], v158 offset:3072
	v_add_u32_e32 v158, s65, v145
	ds_read_b128 v[168:171], v158
	ds_read_b128 v[172:175], v158 offset:1024
	ds_read_b128 v[176:179], v158 offset:2048
	ds_read_b128 v[180:183], v158 offset:3072
	s_add_u32 s30, s42, 0x80000
	s_addc_u32 s31, s43, 0
	s_mov_b32 m0, s60
	v_lshl_add_u64 v[228:229], s[30:31], 0, v[134:135]
	ds_read_b128 v[184:187], v147 offset:32768
	ds_read_b128 v[188:191], v147 offset:33792
	ds_read_b128 v[192:195], v147 offset:34816
	ds_read_b128 v[204:207], v147 offset:35840
	ds_read_b128 v[208:211], v147 offset:36864
	ds_read_b128 v[212:215], v147 offset:37888
	ds_read_b128 v[216:219], v147 offset:38912
	ds_read_b128 v[220:223], v147 offset:39936
	global_load_lds_dwordx4 v[228:229], off
	v_lshl_add_u64 v[228:229], s[30:31], 0, v[132:133]
	s_mov_b32 m0, s61
	s_nop 0
	global_load_lds_dwordx4 v[228:229], off
	s_waitcnt vmcnt(8)
	s_waitcnt lgkmcnt(0)
	s_barrier
	s_setprio 1
	s_waitcnt lgkmcnt(0)
	v_mfma_f32_16x16x32_bf16 v[128:131], v[140:143], v[184:187], v[128:131]
	v_mfma_f32_16x16x32_bf16 v[128:131], v[148:151], v[188:191], v[128:131]
	v_mfma_f32_16x16x32_bf16 v[124:127], v[152:155], v[184:187], v[124:127]
	v_mfma_f32_16x16x32_bf16 v[124:127], v[164:167], v[188:191], v[124:127]
	v_mfma_f32_16x16x32_bf16 v[120:123], v[140:143], v[192:195], v[120:123]
	v_mfma_f32_16x16x32_bf16 v[120:123], v[148:151], v[204:207], v[120:123]
	v_mfma_f32_16x16x32_bf16 v[112:115], v[152:155], v[192:195], v[112:115]
	v_mfma_f32_16x16x32_bf16 v[112:115], v[164:167], v[204:207], v[112:115]
	v_mfma_f32_16x16x32_bf16 v[104:107], v[140:143], v[208:211], v[104:107]
	v_mfma_f32_16x16x32_bf16 v[104:107], v[148:151], v[212:215], v[104:107]
	v_mfma_f32_16x16x32_bf16 v[96:99], v[152:155], v[208:211], v[96:99]
	v_mfma_f32_16x16x32_bf16 v[96:99], v[164:167], v[212:215], v[96:99]
	v_mfma_f32_16x16x32_bf16 v[88:91], v[140:143], v[216:219], v[88:91]
	v_mfma_f32_16x16x32_bf16 v[88:91], v[148:151], v[220:223], v[88:91]
	v_mfma_f32_16x16x32_bf16 v[80:83], v[152:155], v[216:219], v[80:83]
	v_mfma_f32_16x16x32_bf16 v[80:83], v[164:167], v[220:223], v[80:83]
	s_setprio 0
	s_setprio 1
	v_mfma_f32_16x16x32_bf16 v[116:119], v[168:171], v[184:187], v[116:119]
	v_mfma_f32_16x16x32_bf16 v[116:119], v[172:175], v[188:191], v[116:119]
	v_mfma_f32_16x16x32_bf16 v[108:111], v[176:179], v[184:187], v[108:111]
	v_mfma_f32_16x16x32_bf16 v[108:111], v[180:183], v[188:191], v[108:111]
	v_mfma_f32_16x16x32_bf16 v[100:103], v[168:171], v[192:195], v[100:103]
	v_mfma_f32_16x16x32_bf16 v[100:103], v[172:175], v[204:207], v[100:103]
	v_mfma_f32_16x16x32_bf16 v[92:95], v[176:179], v[192:195], v[92:95]
	v_mfma_f32_16x16x32_bf16 v[92:95], v[180:183], v[204:207], v[92:95]
	v_mfma_f32_16x16x32_bf16 v[84:87], v[168:171], v[208:211], v[84:87]
	v_mfma_f32_16x16x32_bf16 v[84:87], v[172:175], v[212:215], v[84:87]
	v_mfma_f32_16x16x32_bf16 v[76:79], v[176:179], v[208:211], v[76:79]
	v_mfma_f32_16x16x32_bf16 v[76:79], v[180:183], v[212:215], v[76:79]
	v_mfma_f32_16x16x32_bf16 v[72:75], v[168:171], v[216:219], v[72:75]
	v_mfma_f32_16x16x32_bf16 v[72:75], v[172:175], v[220:223], v[72:75]
	s_setprio 2
	s_barrier
; #define PG8_STAGE(bufoff, gbase, voff) do { _Pragma("unroll") for (int _i = 0; _i < 2; ++_i) \
;         __builtin_amdgcn_global_load_lds((const unsigned*)((const char*)(gbase) + (voff)[_i]), (LAS unsigned*)(lds + (bufoff) + ldsw + _i * 8192), 16, 0, 0); } while (0)
; #define PG8_LDA(dst, b, h) do { _Pragma("unroll") for (int m = 0; m < 4; ++m) _Pragma("unroll") for (int k = 0; k < 2; ++k) dst[m][k] = *(const LAS bf16x8*)(lds + PG8_SA(b, h) + aoff + m * 2048 + k * 1024); } while (0)
; #define PG8_MMA(ai, bj, At, Bt) do { __builtin_amdgcn_s_setprio(1); _Pragma("unroll") for (int m = 0; m < 4; ++m) _Pragma("unroll") for (int n = 0; n < 2; ++n) _Pragma("unroll") for (int k = 0; k < 2; ++k) \
;         acc[ai][bj][m][n] = __builtin_amdgcn_mfma_f32_16x16x32_bf16(Bt[n][k], At[m][k], acc[ai][bj][m][n], 0, 0, 0); __builtin_amdgcn_s_setprio(0); } while (0)
; #define PG8_WAIT_V(n) asm volatile("s_waitcnt vmcnt(" #n ")" ::: "memory")
; #define PG8_WAIT_L(n) asm volatile("s_waitcnt lgkmcnt(" #n ")" ::: "memory")
; #define PG8_BAR __builtin_amdgcn_s_barrier()
; #define PG8_SCHED __builtin_amdgcn_sched_barrier(0)
; template <class Epi, class Sched, bool ALIGN_EPI = true>
; __device__ __forceinline__ void gemm_phase(LAS unsigned char* lds, const Gemm g, const Sched& S, const Epi& E) {
;     ...
;             PG8_LDA(At, 1, 1); PG8_STAGE(PG8_SB(1, 0), b3, voffB); PG8_STAGE(PG8_SB(1, 1), b3 + hB, voffB); PG8_STAGE(PG8_SA(1, 0), a3, voffA);
;             PG8_WAIT_V(8); PG8_WAIT_L(0); PG8_BAR; PG8_MMA(1, 0, At, B0); PG8_MMA(1, 1, At, B1); PG8_BAR; PG8_SCHED;
;         }
	v_mfma_f32_16x16x32_bf16 v[68:71], v[176:179], v[216:219], v[68:71]
	v_mfma_f32_16x16x32_bf16 v[68:71], v[180:183], v[220:223], v[68:71]
	s_setprio 0
	s_add_i32 s27, s27, s53
	v_lshl_add_u64 v[156:157], v[156:157], 0, s[86:87]
	s_mov_b32 m0, s27
	ds_read_b128 v[184:187], v147 offset:49152
	ds_read_b128 v[188:191], v147 offset:50176
	ds_read_b128 v[192:195], v147 offset:51200
	ds_read_b128 v[204:207], v147 offset:52224
	ds_read_b128 v[208:211], v147 offset:53248
	ds_read_b128 v[212:215], v147 offset:54272
	ds_read_b128 v[216:219], v147 offset:55296
	ds_read_b128 v[220:223], v147 offset:56320
	global_load_lds_dwordx4 v[156:157], off
	s_add_i32 m0, s27, 0x2000
	s_add_u32 s30, s40, 0x80080
	v_lshl_add_u64 v[156:157], v[196:197], 0, s[86:87]
	s_addc_u32 s31, s41, 0
	s_add_i32 s27, s65, s53
	global_load_lds_dwordx4 v[156:157], off
	v_lshl_add_u64 v[156:157], s[30:31], 0, v[2:3]
	s_mov_b32 m0, s27
	s_nop 0
	global_load_lds_dwordx4 v[156:157], off
	v_lshl_add_u64 v[156:157], s[30:31], 0, v[0:1]
	s_add_i32 m0, s27, 0x2000
	s_nop 0
	global_load_lds_dwordx4 v[156:157], off
	v_lshl_add_u64 v[156:157], v[224:225], 0, s[86:87]
	s_mov_b32 m0, s62
	s_nop 0
	global_load_lds_dwordx4 v[156:157], off
	v_lshl_add_u64 v[156:157], v[226:227], 0, s[86:87]
	s_mov_b32 m0, s63
	s_nop 0
	global_load_lds_dwordx4 v[156:157], off
	s_waitcnt vmcnt(8)
	s_waitcnt lgkmcnt(0)
	s_barrier
	s_setprio 1
	s_waitcnt lgkmcnt(0)
	v_mfma_f32_16x16x32_bf16 v[64:67], v[140:143], v[184:187], v[64:67]
	v_mfma_f32_16x16x32_bf16 v[64:67], v[148:151], v[188:191], v[64:67]
	v_mfma_f32_16x16x32_bf16 v[60:63], v[152:155], v[184:187], v[60:63]
	v_mfma_f32_16x16x32_bf16 v[60:63], v[164:167], v[188:191], v[60:63]
	v_mfma_f32_16x16x32_bf16 v[56:59], v[140:143], v[192:195], v[56:59]
	v_mfma_f32_16x16x32_bf16 v[56:59], v[148:151], v[204:207], v[56:59]
	v_mfma_f32_16x16x32_bf16 v[48:51], v[152:155], v[192:195], v[48:51]
	v_mfma_f32_16x16x32_bf16 v[48:51], v[164:167], v[204:207], v[48:51]
	v_mfma_f32_16x16x32_bf16 v[40:43], v[140:143], v[208:211], v[40:43]
	v_mfma_f32_16x16x32_bf16 v[40:43], v[148:151], v[212:215], v[40:43]
	v_mfma_f32_16x16x32_bf16 v[32:35], v[152:155], v[208:211], v[32:35]
	v_mfma_f32_16x16x32_bf16 v[32:35], v[164:167], v[212:215], v[32:35]
	v_mfma_f32_16x16x32_bf16 v[24:27], v[140:143], v[216:219], v[24:27]
	v_mfma_f32_16x16x32_bf16 v[24:27], v[148:151], v[220:223], v[24:27]
	v_mfma_f32_16x16x32_bf16 v[16:19], v[152:155], v[216:219], v[16:19]
	v_mfma_f32_16x16x32_bf16 v[16:19], v[164:167], v[220:223], v[16:19]
	s_setprio 0
	s_setprio 1
	v_mfma_f32_16x16x32_bf16 v[52:55], v[168:171], v[184:187], v[52:55]
	v_mfma_f32_16x16x32_bf16 v[52:55], v[172:175], v[188:191], v[52:55]
	v_mfma_f32_16x16x32_bf16 v[44:47], v[176:179], v[184:187], v[44:47]
	v_mfma_f32_16x16x32_bf16 v[44:47], v[180:183], v[188:191], v[44:47]
	v_mfma_f32_16x16x32_bf16 v[36:39], v[168:171], v[192:195], v[36:39]
	v_mfma_f32_16x16x32_bf16 v[36:39], v[172:175], v[204:207], v[36:39]
	v_mfma_f32_16x16x32_bf16 v[28:31], v[176:179], v[192:195], v[28:31]
	v_mfma_f32_16x16x32_bf16 v[28:31], v[180:183], v[204:207], v[28:31]
	v_mfma_f32_16x16x32_bf16 v[20:23], v[168:171], v[208:211], v[20:23]
	v_mfma_f32_16x16x32_bf16 v[20:23], v[172:175], v[212:215], v[20:23]
	v_mfma_f32_16x16x32_bf16 v[12:15], v[176:179], v[208:211], v[12:15]
	v_mfma_f32_16x16x32_bf16 v[12:15], v[180:183], v[212:215], v[12:15]
	v_mfma_f32_16x16x32_bf16 v[8:11], v[168:171], v[216:219], v[8:11]
	v_mfma_f32_16x16x32_bf16 v[8:11], v[172:175], v[220:223], v[8:11]
	s_setprio 2
	s_barrier
	v_mfma_f32_16x16x32_bf16 v[4:7], v[176:179], v[216:219], v[4:7]
	v_mfma_f32_16x16x32_bf16 v[4:7], v[180:183], v[220:223], v[4:7]
	s_setprio 0
	s_add_i32 s26, s26, 2
	s_add_u32 s38, s38, 0x100
	s_addc_u32 s39, s39, 0
	s_add_u32 s24, s24, 0x100
	s_addc_u32 s25, s25, 0
	s_cmp_gt_u32 s26, 29
	s_cbranch_scc1 .Lpeel_exit_218

; __device__ __forceinline__ unsigned pk2(float lo, float hi) { f32x2 v = {lo, hi}; bf16x2_t b = __builtin_convertvector(v, bf16x2_t); return __builtin_bit_cast(unsigned, b); }
;     __device__ __forceinline__ void operator()(f32x4 (&acc)[2][2][4][2], const Unit& u, int wr, int wc, int fr, int fq, int wid, int lane) const {
;     ...
;             for (int m = 0; m < 4; ++m) { bf16_t* rowp = O + (size_t)(row0 + ai * HALF + m * 16) * ldc + col0;
; #pragma unroll
;                 for (int bj = 0; bj < 2; ++bj) { f32x4 v0 = (acc[ai][bj][m][0] + bv[bj][0]) * sv[bj][0], v1 = (acc[ai][bj][m][1] + bv[bj][1]) * sv[bj][1];
;                     u32x4 w; w.x = pk2(v0[0], v0[1]); w.y = pk2(v0[2], v0[3]); w.z = pk2(v1[0], v1[1]); w.w = pk2(v1[2], v1[3]);
;                     *(u32x4*)(rowp + bj * HALF) = w; } }
.LBB0_221:
	s_waitcnt vmcnt(0)
	v_lshl_or_b32 v142, s17, 8, v146
	v_ashrrev_i32_e32 v143, 31, v142
	v_lshl_add_u32 v152, s16, 8, v144
	v_mov_b64_e32 v[140:141], s[82:83]
	v_mad_i64_i32 v[148:149], s[16:17], v152, s91, v[140:141]
	v_lshlrev_b64 v[142:143], 1, v[142:143]
	v_pk_add_f32 v[130:131], v[130:131], 0 op_sel_hi:[1,0]
	v_pk_add_f32 v[128:129], v[128:129], 0 op_sel_hi:[1,0]
	v_pk_add_f32 v[150:151], v[126:127], 0 op_sel_hi:[1,0]
	v_pk_add_f32 v[126:127], v[124:125], 0 op_sel_hi:[1,0]
	v_lshl_add_u64 v[148:149], v[148:149], 0, v[142:143]
	v_cvt_pk_bf16_f32 v124, v128, v129
	v_cvt_pk_bf16_f32 v125, v130, v131
	v_cvt_pk_bf16_f32 v126, v126, v127
	v_cvt_pk_bf16_f32 v127, v150, v151
	global_store_dwordx4 v[148:149], v[124:127], off
	v_pk_add_f32 v[118:119], v[118:119], 0 op_sel_hi:[1,0]
	v_pk_add_f32 v[116:117], v[116:117], 0 op_sel_hi:[1,0]
	v_pk_add_f32 v[124:125], v[110:111], 0 op_sel_hi:[1,0]
	v_pk_add_f32 v[110:111], v[108:109], 0 op_sel_hi:[1,0]
	v_cvt_pk_bf16_f32 v108, v116, v117
	v_cvt_pk_bf16_f32 v109, v118, v119
	v_cvt_pk_bf16_f32 v110, v110, v111
	v_cvt_pk_bf16_f32 v111, v124, v125
	global_store_dwordx4 v[148:149], v[108:111], off offset:256
	v_pk_add_f32 v[114:115], v[114:115], 0 op_sel_hi:[1,0]
	v_pk_add_f32 v[112:113], v[112:113], 0 op_sel_hi:[1,0]
	v_or_b32_e32 v108, 16, v152
	v_mad_i64_i32 v[108:109], s[16:17], v108, s91, v[140:141]
	v_lshl_add_u64 v[116:117], v[108:109], 0, v[142:143]
	v_pk_add_f32 v[110:111], v[122:123], 0 op_sel_hi:[1,0]
	v_pk_add_f32 v[108:109], v[120:121], 0 op_sel_hi:[1,0]
	v_pk_add_f32 v[102:103], v[102:103], 0 op_sel_hi:[1,0]
	v_cvt_pk_bf16_f32 v108, v108, v109
	v_cvt_pk_bf16_f32 v109, v110, v111
	v_cvt_pk_bf16_f32 v110, v112, v113
	v_cvt_pk_bf16_f32 v111, v114, v115
	global_store_dwordx4 v[116:117], v[108:111], off
	v_pk_add_f32 v[100:101], v[100:101], 0 op_sel_hi:[1,0]
	v_pk_add_f32 v[98:99], v[98:99], 0 op_sel_hi:[1,0]
	v_pk_add_f32 v[108:109], v[94:95], 0 op_sel_hi:[1,0]
	v_pk_add_f32 v[94:95], v[92:93], 0 op_sel_hi:[1,0]
	v_cvt_pk_bf16_f32 v92, v100, v101
	v_cvt_pk_bf16_f32 v93, v102, v103
	v_cvt_pk_bf16_f32 v94, v94, v95
	v_cvt_pk_bf16_f32 v95, v108, v109
	global_store_dwordx4 v[116:117], v[92:95], off offset:256
	v_pk_add_f32 v[96:97], v[96:97], 0 op_sel_hi:[1,0]
	v_pk_add_f32 v[86:87], v[86:87], 0 op_sel_hi:[1,0]
	v_or_b32_e32 v92, 32, v152
	v_mad_i64_i32 v[92:93], s[16:17], v92, s91, v[140:141]
	v_lshl_add_u64 v[100:101], v[92:93], 0, v[142:143]
	v_pk_add_f32 v[94:95], v[106:107], 0 op_sel_hi:[1,0]
	v_pk_add_f32 v[92:93], v[104:105], 0 op_sel_hi:[1,0]
	v_pk_add_f32 v[84:85], v[84:85], 0 op_sel_hi:[1,0]
	v_cvt_pk_bf16_f32 v92, v92, v93
	v_cvt_pk_bf16_f32 v93, v94, v95
	v_cvt_pk_bf16_f32 v94, v96, v97
	v_cvt_pk_bf16_f32 v95, v98, v99
	global_store_dwordx4 v[100:101], v[92:95], off
	v_pk_add_f32 v[82:83], v[82:83], 0 op_sel_hi:[1,0]
	v_pk_add_f32 v[80:81], v[80:81], 0 op_sel_hi:[1,0]
	v_pk_add_f32 v[92:93], v[78:79], 0 op_sel_hi:[1,0]
	v_pk_add_f32 v[78:79], v[76:77], 0 op_sel_hi:[1,0]
	v_cvt_pk_bf16_f32 v76, v84, v85
	v_cvt_pk_bf16_f32 v77, v86, v87
	v_cvt_pk_bf16_f32 v78, v78, v79
	v_cvt_pk_bf16_f32 v79, v92, v93
	global_store_dwordx4 v[100:101], v[76:79], off offset:256
	v_pk_add_f32 v[74:75], v[74:75], 0 op_sel_hi:[1,0]
	v_pk_add_f32 v[72:73], v[72:73], 0 op_sel_hi:[1,0]
	v_or_b32_e32 v76, 48, v152
	v_mad_i64_i32 v[76:77], s[16:17], v76, s91, v[140:141]
	v_lshl_add_u64 v[84:85], v[76:77], 0, v[142:143]
	v_pk_add_f32 v[78:79], v[90:91], 0 op_sel_hi:[1,0]
	v_pk_add_f32 v[76:77], v[88:89], 0 op_sel_hi:[1,0]
	v_pk_add_f32 v[66:67], v[66:67], 0 op_sel_hi:[1,0]
	v_cvt_pk_bf16_f32 v76, v76, v77
	v_cvt_pk_bf16_f32 v77, v78, v79
	v_cvt_pk_bf16_f32 v78, v80, v81
	v_cvt_pk_bf16_f32 v79, v82, v83
	global_store_dwordx4 v[84:85], v[76:79], off
	v_pk_add_f32 v[64:65], v[64:65], 0 op_sel_hi:[1,0]
	v_pk_add_f32 v[54:55], v[54:55], 0 op_sel_hi:[1,0]
	v_pk_add_f32 v[76:77], v[70:71], 0 op_sel_hi:[1,0]
	v_pk_add_f32 v[70:71], v[68:69], 0 op_sel_hi:[1,0]
; __device__ __forceinline__ unsigned pk2(float lo, float hi) { f32x2 v = {lo, hi}; bf16x2_t b = __builtin_convertvector(v, bf16x2_t); return __builtin_bit_cast(unsigned, b); }
; #define PG8_BAR __builtin_amdgcn_s_barrier()
;     __device__ __forceinline__ void operator()(f32x4 (&acc)[2][2][4][2], const Unit& u, int wr, int wc, int fr, int fq, int wid, int lane) const {
;     ...
;             for (int m = 0; m < 4; ++m) { bf16_t* rowp = O + (size_t)(row0 + ai * HALF + m * 16) * ldc + col0;
; #pragma unroll
;                 for (int bj = 0; bj < 2; ++bj) { f32x4 v0 = (acc[ai][bj][m][0] + bv[bj][0]) * sv[bj][0], v1 = (acc[ai][bj][m][1] + bv[bj][1]) * sv[bj][1];
;                     u32x4 w; w.x = pk2(v0[0], v0[1]); w.y = pk2(v0[2], v0[3]); w.z = pk2(v1[0], v1[1]); w.w = pk2(v1[2], v1[3]);
;                     *(u32x4*)(rowp + bj * HALF) = w; } }
; template <class Epi, class Sched, bool ALIGN_EPI = true>
; __device__ __forceinline__ void gemm_phase(LAS unsigned char* lds, const Gemm g, const Sched& S, const Epi& E) {
;     ...
;         if (!has_next) break;
; #pragma unroll
;         for (int a = 0; a < 2; ++a)
; #pragma unroll
;             for (int b = 0; b < 2; ++b)
; #pragma unroll
;                 for (int m = 0; m < 4; ++m)
; #pragma unroll
;                     for (int n = 0; n < 2; ++n) acc[a][b][m][n] = (f32x4){0.f, 0.f, 0.f, 0.f};
;         cur = nxt; cA = nA; cB = nB; ++ui;
;         if constexpr (ALIGN_EPI) { if (wr == 1) PG8_BAR; }
	v_cvt_pk_bf16_f32 v68, v72, v73
	v_cvt_pk_bf16_f32 v69, v74, v75
	v_cvt_pk_bf16_f32 v70, v70, v71
	v_cvt_pk_bf16_f32 v71, v76, v77
	global_store_dwordx4 v[84:85], v[68:71], off offset:256
	v_pk_add_f32 v[52:53], v[52:53], 0 op_sel_hi:[1,0]
	v_pk_add_f32 v[50:51], v[50:51], 0 op_sel_hi:[1,0]
	v_add_u32_e32 v68, 0x80, v152
	v_mad_i64_i32 v[68:69], s[16:17], v68, s91, v[140:141]
	v_pk_add_f32 v[70:71], v[62:63], 0 op_sel_hi:[1,0]
	v_pk_add_f32 v[62:63], v[60:61], 0 op_sel_hi:[1,0]
	v_lshl_add_u64 v[68:69], v[68:69], 0, v[142:143]
	v_cvt_pk_bf16_f32 v60, v64, v65
	v_cvt_pk_bf16_f32 v61, v66, v67
	v_cvt_pk_bf16_f32 v62, v62, v63
	v_cvt_pk_bf16_f32 v63, v70, v71
	global_store_dwordx4 v[68:69], v[60:63], off
	v_pk_add_f32 v[48:49], v[48:49], 0 op_sel_hi:[1,0]
	v_pk_add_f32 v[38:39], v[38:39], 0 op_sel_hi:[1,0]
	v_pk_add_f32 v[60:61], v[46:47], 0 op_sel_hi:[1,0]
	v_pk_add_f32 v[46:47], v[44:45], 0 op_sel_hi:[1,0]
	v_cvt_pk_bf16_f32 v44, v52, v53
	v_cvt_pk_bf16_f32 v45, v54, v55
	v_cvt_pk_bf16_f32 v46, v46, v47
	v_cvt_pk_bf16_f32 v47, v60, v61
	global_store_dwordx4 v[68:69], v[44:47], off offset:256
	v_pk_add_f32 v[36:37], v[36:37], 0 op_sel_hi:[1,0]
	v_pk_add_f32 v[34:35], v[34:35], 0 op_sel_hi:[1,0]
	v_add_u32_e32 v44, 0x90, v152
	v_mad_i64_i32 v[44:45], s[16:17], v44, s91, v[140:141]
	v_lshl_add_u64 v[52:53], v[44:45], 0, v[142:143]
	v_pk_add_f32 v[46:47], v[58:59], 0 op_sel_hi:[1,0]
	v_pk_add_f32 v[44:45], v[56:57], 0 op_sel_hi:[1,0]
	v_pk_add_f32 v[32:33], v[32:33], 0 op_sel_hi:[1,0]
	v_cvt_pk_bf16_f32 v44, v44, v45
	v_cvt_pk_bf16_f32 v45, v46, v47
	v_cvt_pk_bf16_f32 v46, v48, v49
	v_cvt_pk_bf16_f32 v47, v50, v51
	global_store_dwordx4 v[52:53], v[44:47], off
	v_pk_add_f32 v[22:23], v[22:23], 0 op_sel_hi:[1,0]
	v_pk_add_f32 v[20:21], v[20:21], 0 op_sel_hi:[1,0]
	v_pk_add_f32 v[44:45], v[30:31], 0 op_sel_hi:[1,0]
	v_pk_add_f32 v[30:31], v[28:29], 0 op_sel_hi:[1,0]
	v_cvt_pk_bf16_f32 v28, v36, v37
	v_cvt_pk_bf16_f32 v29, v38, v39
	v_cvt_pk_bf16_f32 v30, v30, v31
	v_cvt_pk_bf16_f32 v31, v44, v45
	global_store_dwordx4 v[52:53], v[28:31], off offset:256
	v_pk_add_f32 v[18:19], v[18:19], 0 op_sel_hi:[1,0]
	v_pk_add_f32 v[16:17], v[16:17], 0 op_sel_hi:[1,0]
	v_add_u32_e32 v28, 0xa0, v152
	v_mad_i64_i32 v[28:29], s[16:17], v28, s91, v[140:141]
	v_lshl_add_u64 v[36:37], v[28:29], 0, v[142:143]
	v_pk_add_f32 v[30:31], v[42:43], 0 op_sel_hi:[1,0]
	v_pk_add_f32 v[28:29], v[40:41], 0 op_sel_hi:[1,0]
	v_pk_add_f32 v[10:11], v[10:11], 0 op_sel_hi:[1,0]
	v_cvt_pk_bf16_f32 v28, v28, v29
	v_cvt_pk_bf16_f32 v29, v30, v31
	v_cvt_pk_bf16_f32 v30, v32, v33
	v_cvt_pk_bf16_f32 v31, v34, v35
	global_store_dwordx4 v[36:37], v[28:31], off
	v_pk_add_f32 v[8:9], v[8:9], 0 op_sel_hi:[1,0]
	v_readlane_b32 s42, v252, 38
	v_pk_add_f32 v[28:29], v[14:15], 0 op_sel_hi:[1,0]
	v_pk_add_f32 v[14:15], v[12:13], 0 op_sel_hi:[1,0]
	v_cvt_pk_bf16_f32 v12, v20, v21
	v_cvt_pk_bf16_f32 v13, v22, v23
	v_cvt_pk_bf16_f32 v14, v14, v15
	v_cvt_pk_bf16_f32 v15, v28, v29
	global_store_dwordx4 v[36:37], v[12:15], off offset:256
	s_andn2_b64 vcc, exec, s[4:5]
	s_mov_b64 s[4:5], -1
	v_add_u32_e32 v12, 0xb0, v152
	v_mad_i64_i32 v[12:13], s[16:17], v12, s91, v[140:141]
	v_lshl_add_u64 v[20:21], v[12:13], 0, v[142:143]
	v_pk_add_f32 v[14:15], v[26:27], 0 op_sel_hi:[1,0]
	v_pk_add_f32 v[12:13], v[24:25], 0 op_sel_hi:[1,0]
	v_readlane_b32 s43, v252, 39
	v_cvt_pk_bf16_f32 v12, v12, v13
	v_cvt_pk_bf16_f32 v13, v14, v15
	v_cvt_pk_bf16_f32 v14, v16, v17
	v_cvt_pk_bf16_f32 v15, v18, v19
	global_store_dwordx4 v[20:21], v[12:15], off
	s_nop 1
	v_pk_add_f32 v[12:13], v[6:7], 0 op_sel_hi:[1,0]
	v_pk_add_f32 v[6:7], v[4:5], 0 op_sel_hi:[1,0]
	v_cvt_pk_bf16_f32 v4, v8, v9
	v_cvt_pk_bf16_f32 v5, v10, v11
	v_cvt_pk_bf16_f32 v6, v6, v7
	v_cvt_pk_bf16_f32 v7, v12, v13
	global_store_dwordx4 v[20:21], v[4:7], off offset:256
	s_cbranch_vccnz .LBB0_214
	s_andn2_b64 vcc, exec, s[2:3]
	s_cbranch_vccnz .LBB0_213
	s_barrier
	s_branch .LBB0_213

;     __device__ bool next(int i, Unit& u) const { if (i >= 2) return false; const int x = c & 7, j = c >> 3; u.pm = 32 * i + 4 * x + (j & 3); u.pn = j >> 2; return true; }
; #define PG8_STAGE(bufoff, gbase, voff) do { _Pragma("unroll") for (int _i = 0; _i < 2; ++_i) \
;         __builtin_amdgcn_global_load_lds((const unsigned*)((const char*)(gbase) + (voff)[_i]), (LAS unsigned*)(lds + (bufoff) + ldsw + _i * 8192), 16, 0, 0); } while (0)
; #define PG8_WAIT_V(n) asm volatile("s_waitcnt vmcnt(" #n ")" ::: "memory")
; #define PG8_WAIT_L(n) asm volatile("s_waitcnt lgkmcnt(" #n ")" ::: "memory")
; #define PG8_BAR __builtin_amdgcn_s_barrier()
;     __device__ __forceinline__ void operator()(f32x4 (&acc)[2][2][4][2], const Unit& u, int wr, int wc, int fr_, int fq_, int wid, int lane_) const {
;     ...
;             const int t = wid * 64 + lane, kind = t >> 6, pr = t & 63, bj = kind >> 2, tap = kind & 3;
;             const float* src = (tap < 3) ? (cw + (size_t)tap * FF2 + bj * FF + u.pn * 128 + 2 * pr) : (cb + bj * FF + u.pn * 128 + 2 * pr);
;             const f32x2 wv = *(const f32x2*)src;
; template <class Epi, class Sched, bool ALIGN_EPI = true>
; __device__ __forceinline__ void gemm_phase(LAS unsigned char* lds, const Gemm g, const Sched& S, const Epi& E) {
;     ...
;         const bool has_next = S.next(ui + 1, nxt);
;         const char* nA = has_next ? (const char*)g.A + ((size_t)nxt.pm * BM * g.lda + (size_t)nxt.pn * g.a_pn_off) * 2 : cA; const char* nB = has_next ? (const char*)g.Bt + (size_t)nxt.pn * BM * g.ldb * 2 : cB;
;         for (int t = 0; t < nt; t += 2) {
;             const bool last = (t == nt - 2);
;             const char* a1 = cA + (size_t)(t + 1) * kstep;
;             const char* a2 = last ? nA : cA + (size_t)(t + 2) * kstep; const char* b2 = last ? nB : cB + (size_t)(t + 2) * kstep;
;             const char* a3 = a2 + kstep; const char* b3 = b2 + kstep;
;             PG8_LDB(B0, 0, 0); PG8_LDB(B1, 0, 1); PG8_SCHED; PG8_LDA(At, 0, 0); PG8_STAGE(PG8_SA(1, 1), a1 + hA, voffA);
;             PG8_WAIT_V(8); PG8_WAIT_L(0); PG8_BAR; PG8_MMA(0, 0, At, B0); PG8_MMA(0, 1, At, B1); PG8_BAR; PG8_SCHED;
;             PG8_LDA(At, 0, 1); PG8_STAGE(PG8_SB(0, 0), b2, voffB); PG8_STAGE(PG8_SB(0, 1), b2 + hB, voffB); PG8_STAGE(PG8_SA(0, 0), a2, voffA);
;             PG8_WAIT_V(8); PG8_WAIT_L(0); PG8_BAR; PG8_MMA(1, 0, At, B0); PG8_MMA(1, 1, At, B1); PG8_BAR; PG8_SCHED;
.LBB0_827:
	s_ashr_i32 s39, s38, 31
	s_lshl_b64 s[16:17], s[38:39], 20
	s_add_u32 s40, s46, s16
	s_addc_u32 s41, s47, s17
	s_and_b64 s[16:17], s[4:5], exec
	s_cselect_b32 s16, s41, s7
	s_cselect_b32 s17, s40, s6
	s_ashr_i32 s15, s14, 31
	s_lshl_b64 s[18:19], s[14:15], 20
	s_add_u32 s42, s53, s18
	s_addc_u32 s43, s60, s19
	s_and_b64 s[18:19], s[4:5], exec
	s_cselect_b32 s15, s43, s45
	s_cselect_b32 s18, s42, s44
	s_add_u32 s6, s6, 0x80080
	s_addc_u32 s7, s7, 0
	s_add_u32 s19, s44, 0x100
	s_addc_u32 s24, s45, 0
	s_mov_b32 s25, -2
	v_add_u32_e32 v228, s77, v158
	v_ashrrev_i32_e32 v229, 6, v228
	v_and_b32_e32 v230, 3, v229
	v_lshrrev_b32_e32 v231, 8, v228
	v_mul_u32_u24_e32 v228, 0x2c00, v230
	v_lshlrev_b32_e32 v228, 2, v228
	v_mov_b32_e32 v229, 0
	v_lshl_add_u64 v[232:233], s[2:3], 0, v[228:229]
	v_mov_b32_e32 v228, s9
	v_cmp_eq_u32_e32 vcc, 3, v230
	v_mul_i32_i24_e32 v234, 0x1600, v231
	v_ashrrev_i32_e32 v235, 31, v234
	v_cndmask_b32_e32 v233, v233, v228, vcc
	v_mov_b32_e32 v228, s8
	v_cndmask_b32_e32 v232, v232, v228, vcc
	v_lshl_add_u64 v[232:233], v[234:235], 2, v[232:233]
	s_lshl_b32 s26, s82, 7
	s_ashr_i32 s27, s26, 31
	v_lshl_add_u64 v[232:233], s[26:27], 2, v[232:233]
	v_and_b32_e32 v228, 63, v158
	v_lshlrev_b32_e32 v228, 3, v228
	v_mov_b32_e32 v229, 0
	v_lshl_add_u64 v[232:233], v[232:233], 0, v[228:229]
	global_load_dwordx2 v[226:227], v[232:233], off
	s_add_u32 s26, s6, 0xfff80080
	s_addc_u32 s27, s7, -1
	s_add_i32 s30, 0, 0x10000
	s_cmp_eq_u32 s25, 28
	s_cselect_b32 s59, s16, s27
	s_cselect_b32 s58, s17, s26
	v_add_u32_e32 v2, s30, v204
	s_cselect_b32 s45, s15, s24
	s_cselect_b32 s44, s18, s19
	s_add_i32 s31, 0, 0x14000
	ds_read_b128 v[132:135], v2
	ds_read_b128 v[136:139], v2 offset:1024
	ds_read_b128 v[140:143], v2 offset:2048
	ds_read_b128 v[144:147], v2 offset:3072
	v_add_u32_e32 v2, s31, v204
	ds_read_b128 v[148:151], v2
	ds_read_b128 v[152:155], v2 offset:1024
	ds_read_b128 v[174:177], v2 offset:2048
	ds_read_b128 v[178:181], v2 offset:3072
	v_lshl_add_u64 v[156:157], s[6:7], 0, v[170:171]
	s_add_i32 m0, s62, 0xc000
	ds_read_b128 v[182:185], v205
	ds_read_b128 v[186:189], v205 offset:1024
	ds_read_b128 v[190:193], v205 offset:2048
	ds_read_b128 v[194:197], v205 offset:3072
	ds_read_b128 v[206:209], v205 offset:4096
	ds_read_b128 v[210:213], v205 offset:5120
	ds_read_b128 v[214:217], v205 offset:6144
	ds_read_b128 v[218:221], v205 offset:7168
	global_load_lds_dwordx4 v[156:157], off
	v_lshl_add_u64 v[156:157], s[6:7], 0, v[172:173]
	s_add_i32 m0, s62, 0xe000
	s_nop 0
	global_load_lds_dwordx4 v[156:157], off
	s_cmp_gt_u32 s80, 1
	s_cbranch_scc1 .Lpw_828_0
	s_waitcnt vmcnt(8)
.Lpw_828_0:
	s_waitcnt lgkmcnt(0)
	s_barrier
	s_setprio 1
	s_waitcnt lgkmcnt(0)
	v_mfma_f32_16x16x32_bf16 v[116:119], v[132:135], v[182:185], 0
	v_mfma_f32_16x16x32_bf16 v[116:119], v[136:139], v[186:189], v[116:119]
	v_mfma_f32_16x16x32_bf16 v[100:103], v[140:143], v[182:185], 0
	v_mfma_f32_16x16x32_bf16 v[100:103], v[144:147], v[186:189], v[100:103]
	v_mfma_f32_16x16x32_bf16 v[108:111], v[132:135], v[190:193], 0
	v_mfma_f32_16x16x32_bf16 v[108:111], v[136:139], v[194:197], v[108:111]
	v_mfma_f32_16x16x32_bf16 v[96:99], v[140:143], v[190:193], 0
	v_mfma_f32_16x16x32_bf16 v[96:99], v[144:147], v[194:197], v[96:99]
	v_mfma_f32_16x16x32_bf16 v[88:91], v[132:135], v[206:209], 0
	v_mfma_f32_16x16x32_bf16 v[88:91], v[136:139], v[210:213], v[88:91]
	v_mfma_f32_16x16x32_bf16 v[84:87], v[140:143], v[206:209], 0
	v_mfma_f32_16x16x32_bf16 v[84:87], v[144:147], v[210:213], v[84:87]
	v_mfma_f32_16x16x32_bf16 v[72:75], v[132:135], v[214:217], 0
	v_mfma_f32_16x16x32_bf16 v[72:75], v[136:139], v[218:221], v[72:75]
	v_mfma_f32_16x16x32_bf16 v[80:83], v[140:143], v[214:217], 0
	v_mfma_f32_16x16x32_bf16 v[80:83], v[144:147], v[218:221], v[80:83]
	s_setprio 0
	s_setprio 1
	v_mfma_f32_16x16x32_bf16 v[128:131], v[148:151], v[182:185], 0
	v_mfma_f32_16x16x32_bf16 v[128:131], v[152:155], v[186:189], v[128:131]
	v_mfma_f32_16x16x32_bf16 v[44:47], v[174:177], v[182:185], 0
	v_mfma_f32_16x16x32_bf16 v[44:47], v[178:181], v[186:189], v[44:47]
	v_mfma_f32_16x16x32_bf16 v[124:127], v[148:151], v[190:193], 0
	v_mfma_f32_16x16x32_bf16 v[124:127], v[152:155], v[194:197], v[124:127]
	v_mfma_f32_16x16x32_bf16 v[36:39], v[174:177], v[190:193], 0
	v_mfma_f32_16x16x32_bf16 v[36:39], v[178:181], v[194:197], v[36:39]
	v_mfma_f32_16x16x32_bf16 v[120:123], v[148:151], v[206:209], 0
	v_mfma_f32_16x16x32_bf16 v[120:123], v[152:155], v[210:213], v[120:123]
	v_mfma_f32_16x16x32_bf16 v[32:35], v[174:177], v[206:209], 0
	v_mfma_f32_16x16x32_bf16 v[32:35], v[178:181], v[210:213], v[32:35]
	v_mfma_f32_16x16x32_bf16 v[112:115], v[148:151], v[214:217], 0
	v_mfma_f32_16x16x32_bf16 v[112:115], v[152:155], v[218:221], v[112:115]
	s_setprio 2
	s_barrier
	v_mfma_f32_16x16x32_bf16 v[28:31], v[174:177], v[214:217], 0
	v_mfma_f32_16x16x32_bf16 v[28:31], v[178:181], v[218:221], v[28:31]
	s_setprio 0
	s_add_i32 s26, s30, s61
	v_lshl_add_u64 v[156:157], s[44:45], 0, v[166:167]
	s_mov_b32 m0, s26
	ds_read_b128 v[182:185], v205 offset:16384
	ds_read_b128 v[186:189], v205 offset:17408
	ds_read_b128 v[190:193], v205 offset:18432
	ds_read_b128 v[194:197], v205 offset:19456
	ds_read_b128 v[206:209], v205 offset:20480
	ds_read_b128 v[210:213], v205 offset:21504
	ds_read_b128 v[214:217], v205 offset:22528
	ds_read_b128 v[218:221], v205 offset:23552
	global_load_lds_dwordx4 v[156:157], off
	s_add_i32 m0, s26, 0x2000
	s_add_u32 s26, s44, 0x80000
	v_lshl_add_u64 v[160:161], s[44:45], 0, v[0:1]
	s_addc_u32 s27, s45, 0
	s_add_i32 s30, s31, s61
	global_load_lds_dwordx4 v[160:161], off
	v_lshl_add_u64 v[162:163], s[26:27], 0, v[166:167]
	s_mov_b32 m0, s30
	v_lshl_add_u64 v[222:223], s[58:59], 0, v[164:165]
	global_load_lds_dwordx4 v[162:163], off
	v_lshl_add_u64 v[162:163], s[26:27], 0, v[0:1]
	s_add_i32 m0, s30, 0x2000
	s_nop 0
	global_load_lds_dwordx4 v[162:163], off
	v_lshl_add_u64 v[162:163], s[58:59], 0, v[168:169]
	s_mov_b32 m0, s62
	s_nop 0
	global_load_lds_dwordx4 v[162:163], off
	s_mov_b32 m0, s63
	s_nop 0
	global_load_lds_dwordx4 v[222:223], off
	s_cmp_gt_u32 s80, 1
	s_cbranch_scc1 .Lpw_828_1
	s_waitcnt vmcnt(8)
; #define PG8_STAGE(bufoff, gbase, voff) do { _Pragma("unroll") for (int _i = 0; _i < 2; ++_i) \
;         __builtin_amdgcn_global_load_lds((const unsigned*)((const char*)(gbase) + (voff)[_i]), (LAS unsigned*)(lds + (bufoff) + ldsw + _i * 8192), 16, 0, 0); } while (0)
; #define PG8_LDA(dst, b, h) do { _Pragma("unroll") for (int m = 0; m < 4; ++m) _Pragma("unroll") for (int k = 0; k < 2; ++k) dst[m][k] = *(const LAS bf16x8*)(lds + PG8_SA(b, h) + aoff + m * 2048 + k * 1024); } while (0)
; #define PG8_LDB(dst, b, h) do { _Pragma("unroll") for (int n = 0; n < 2; ++n) _Pragma("unroll") for (int k = 0; k < 2; ++k) dst[n][k] = *(const LAS bf16x8*)(lds + PG8_SB(b, h) + boff + n * 2048 + k * 1024); } while (0)
; #define PG8_MMA(ai, bj, At, Bt) do { __builtin_amdgcn_s_setprio(1); _Pragma("unroll") for (int m = 0; m < 4; ++m) _Pragma("unroll") for (int n = 0; n < 2; ++n) _Pragma("unroll") for (int k = 0; k < 2; ++k) \
;         acc[ai][bj][m][n] = __builtin_amdgcn_mfma_f32_16x16x32_bf16(Bt[n][k], At[m][k], acc[ai][bj][m][n], 0, 0, 0); __builtin_amdgcn_s_setprio(0); } while (0)
; #define PG8_WAIT_V(n) asm volatile("s_waitcnt vmcnt(" #n ")" ::: "memory")
; #define PG8_WAIT_L(n) asm volatile("s_waitcnt lgkmcnt(" #n ")" ::: "memory")
; #define PG8_BAR __builtin_amdgcn_s_barrier()
; #define PG8_SCHED __builtin_amdgcn_sched_barrier(0)
; template <class Epi, class Sched, bool ALIGN_EPI = true>
; __device__ __forceinline__ void gemm_phase(LAS unsigned char* lds, const Gemm g, const Sched& S, const Epi& E) {
;     ...
;             PG8_WAIT_V(8); PG8_WAIT_L(0); PG8_BAR; PG8_MMA(1, 0, At, B0); PG8_MMA(1, 1, At, B1); PG8_BAR; PG8_SCHED;
;             PG8_LDB(B0, 1, 0); PG8_LDB(B1, 1, 1); PG8_SCHED; PG8_LDA(At, 1, 0); PG8_STAGE(PG8_SA(0, 1), a2 + hA, voffA);
;             PG8_WAIT_V(8); PG8_WAIT_L(0); PG8_BAR; PG8_MMA(0, 0, At, B0); PG8_MMA(0, 1, At, B1); PG8_BAR; PG8_SCHED;
;             PG8_LDA(At, 1, 1); PG8_STAGE(PG8_SB(1, 0), b3, voffB); PG8_STAGE(PG8_SB(1, 1), b3 + hB, voffB); PG8_STAGE(PG8_SA(1, 0), a3, voffA);
;             PG8_WAIT_V(8); PG8_WAIT_L(0); PG8_BAR; PG8_MMA(1, 0, At, B0); PG8_MMA(1, 1, At, B1); PG8_BAR; PG8_SCHED;
.Lpw_828_1:
	s_waitcnt lgkmcnt(0)
	s_barrier
	s_setprio 1
	s_waitcnt lgkmcnt(0)
	v_mfma_f32_16x16x32_bf16 v[60:63], v[132:135], v[182:185], 0
	v_mfma_f32_16x16x32_bf16 v[60:63], v[136:139], v[186:189], v[60:63]
	v_mfma_f32_16x16x32_bf16 v[68:71], v[140:143], v[182:185], 0
	v_mfma_f32_16x16x32_bf16 v[68:71], v[144:147], v[186:189], v[68:71]
	v_mfma_f32_16x16x32_bf16 v[40:43], v[132:135], v[190:193], 0
	v_mfma_f32_16x16x32_bf16 v[40:43], v[136:139], v[194:197], v[40:43]
	v_mfma_f32_16x16x32_bf16 v[64:67], v[140:143], v[190:193], 0
	v_mfma_f32_16x16x32_bf16 v[64:67], v[144:147], v[194:197], v[64:67]
	v_mfma_f32_16x16x32_bf16 v[24:27], v[132:135], v[206:209], 0
	v_mfma_f32_16x16x32_bf16 v[24:27], v[136:139], v[210:213], v[24:27]
	v_mfma_f32_16x16x32_bf16 v[56:59], v[140:143], v[206:209], 0
	v_mfma_f32_16x16x32_bf16 v[56:59], v[144:147], v[210:213], v[56:59]
	v_mfma_f32_16x16x32_bf16 v[12:15], v[132:135], v[214:217], 0
	v_mfma_f32_16x16x32_bf16 v[12:15], v[136:139], v[218:221], v[12:15]
	v_mfma_f32_16x16x32_bf16 v[48:51], v[140:143], v[214:217], 0
	v_mfma_f32_16x16x32_bf16 v[48:51], v[144:147], v[218:221], v[48:51]
	s_setprio 0
	s_setprio 1
	v_mfma_f32_16x16x32_bf16 v[104:107], v[148:151], v[182:185], 0
	v_mfma_f32_16x16x32_bf16 v[104:107], v[152:155], v[186:189], v[104:107]
	v_mfma_f32_16x16x32_bf16 v[20:23], v[174:177], v[182:185], 0
	v_mfma_f32_16x16x32_bf16 v[20:23], v[178:181], v[186:189], v[20:23]
	v_mfma_f32_16x16x32_bf16 v[92:95], v[148:151], v[190:193], 0
	v_mfma_f32_16x16x32_bf16 v[92:95], v[152:155], v[194:197], v[92:95]
	v_mfma_f32_16x16x32_bf16 v[16:19], v[174:177], v[190:193], 0
	v_mfma_f32_16x16x32_bf16 v[16:19], v[178:181], v[194:197], v[16:19]
	v_mfma_f32_16x16x32_bf16 v[76:79], v[148:151], v[206:209], 0
	v_mfma_f32_16x16x32_bf16 v[76:79], v[152:155], v[210:213], v[76:79]
	v_mfma_f32_16x16x32_bf16 v[8:11], v[174:177], v[206:209], 0
	v_mfma_f32_16x16x32_bf16 v[8:11], v[178:181], v[210:213], v[8:11]
	v_mfma_f32_16x16x32_bf16 v[52:55], v[148:151], v[214:217], 0
	v_mfma_f32_16x16x32_bf16 v[52:55], v[152:155], v[218:221], v[52:55]
	s_setprio 2
	s_barrier
	v_mfma_f32_16x16x32_bf16 v[4:7], v[174:177], v[214:217], 0
	v_mfma_f32_16x16x32_bf16 v[4:7], v[178:181], v[218:221], v[4:7]
	s_setprio 0
	s_add_i32 s30, 0, 0x18000
	v_add_u32_e32 v2, s30, v204
	s_add_i32 s31, 0, 0x1c000
	ds_read_b128 v[132:135], v2
	ds_read_b128 v[136:139], v2 offset:1024
	ds_read_b128 v[140:143], v2 offset:2048
	ds_read_b128 v[144:147], v2 offset:3072
	v_add_u32_e32 v2, s31, v204
	ds_read_b128 v[148:151], v2
	ds_read_b128 v[152:155], v2 offset:1024
	ds_read_b128 v[174:177], v2 offset:2048
	ds_read_b128 v[178:181], v2 offset:3072
	s_add_u32 s26, s58, 0x80000
	s_addc_u32 s27, s59, 0
	s_mov_b32 m0, s64
	v_lshl_add_u64 v[224:225], s[26:27], 0, v[168:169]
	ds_read_b128 v[182:185], v205 offset:32768
	ds_read_b128 v[186:189], v205 offset:33792
	ds_read_b128 v[190:193], v205 offset:34816
	ds_read_b128 v[194:197], v205 offset:35840
	ds_read_b128 v[206:209], v205 offset:36864
	ds_read_b128 v[210:213], v205 offset:37888
	ds_read_b128 v[214:217], v205 offset:38912
	ds_read_b128 v[218:221], v205 offset:39936
	global_load_lds_dwordx4 v[224:225], off
	v_lshl_add_u64 v[224:225], s[26:27], 0, v[164:165]
	s_mov_b32 m0, s65
	s_nop 0
	global_load_lds_dwordx4 v[224:225], off
	s_waitcnt vmcnt(8)
	s_waitcnt lgkmcnt(0)
	s_barrier
	s_setprio 1
	s_waitcnt lgkmcnt(0)
	v_mfma_f32_16x16x32_bf16 v[116:119], v[132:135], v[182:185], v[116:119]
	v_mfma_f32_16x16x32_bf16 v[116:119], v[136:139], v[186:189], v[116:119]
	v_mfma_f32_16x16x32_bf16 v[100:103], v[140:143], v[182:185], v[100:103]
	v_mfma_f32_16x16x32_bf16 v[100:103], v[144:147], v[186:189], v[100:103]
	v_mfma_f32_16x16x32_bf16 v[108:111], v[132:135], v[190:193], v[108:111]
	v_mfma_f32_16x16x32_bf16 v[108:111], v[136:139], v[194:197], v[108:111]
	v_mfma_f32_16x16x32_bf16 v[96:99], v[140:143], v[190:193], v[96:99]
	v_mfma_f32_16x16x32_bf16 v[96:99], v[144:147], v[194:197], v[96:99]
	v_mfma_f32_16x16x32_bf16 v[88:91], v[132:135], v[206:209], v[88:91]
	v_mfma_f32_16x16x32_bf16 v[88:91], v[136:139], v[210:213], v[88:91]
	v_mfma_f32_16x16x32_bf16 v[84:87], v[140:143], v[206:209], v[84:87]
	v_mfma_f32_16x16x32_bf16 v[84:87], v[144:147], v[210:213], v[84:87]
	v_mfma_f32_16x16x32_bf16 v[72:75], v[132:135], v[214:217], v[72:75]
	v_mfma_f32_16x16x32_bf16 v[72:75], v[136:139], v[218:221], v[72:75]
	v_mfma_f32_16x16x32_bf16 v[80:83], v[140:143], v[214:217], v[80:83]
	v_mfma_f32_16x16x32_bf16 v[80:83], v[144:147], v[218:221], v[80:83]
	s_setprio 0
	s_setprio 1
	v_mfma_f32_16x16x32_bf16 v[128:131], v[148:151], v[182:185], v[128:131]
	v_mfma_f32_16x16x32_bf16 v[128:131], v[152:155], v[186:189], v[128:131]
	v_mfma_f32_16x16x32_bf16 v[44:47], v[174:177], v[182:185], v[44:47]
	v_mfma_f32_16x16x32_bf16 v[44:47], v[178:181], v[186:189], v[44:47]
	v_mfma_f32_16x16x32_bf16 v[124:127], v[148:151], v[190:193], v[124:127]
	v_mfma_f32_16x16x32_bf16 v[124:127], v[152:155], v[194:197], v[124:127]
	v_mfma_f32_16x16x32_bf16 v[36:39], v[174:177], v[190:193], v[36:39]
	v_mfma_f32_16x16x32_bf16 v[36:39], v[178:181], v[194:197], v[36:39]
	v_mfma_f32_16x16x32_bf16 v[120:123], v[148:151], v[206:209], v[120:123]
	v_mfma_f32_16x16x32_bf16 v[120:123], v[152:155], v[210:213], v[120:123]
	v_mfma_f32_16x16x32_bf16 v[32:35], v[174:177], v[206:209], v[32:35]
	v_mfma_f32_16x16x32_bf16 v[32:35], v[178:181], v[210:213], v[32:35]
	v_mfma_f32_16x16x32_bf16 v[112:115], v[148:151], v[214:217], v[112:115]
	v_mfma_f32_16x16x32_bf16 v[112:115], v[152:155], v[218:221], v[112:115]
	s_setprio 2
	s_barrier
; #define PG8_STAGE(bufoff, gbase, voff) do { _Pragma("unroll") for (int _i = 0; _i < 2; ++_i) \
;         __builtin_amdgcn_global_load_lds((const unsigned*)((const char*)(gbase) + (voff)[_i]), (LAS unsigned*)(lds + (bufoff) + ldsw + _i * 8192), 16, 0, 0); } while (0)
; #define PG8_LDA(dst, b, h) do { _Pragma("unroll") for (int m = 0; m < 4; ++m) _Pragma("unroll") for (int k = 0; k < 2; ++k) dst[m][k] = *(const LAS bf16x8*)(lds + PG8_SA(b, h) + aoff + m * 2048 + k * 1024); } while (0)
; #define PG8_MMA(ai, bj, At, Bt) do { __builtin_amdgcn_s_setprio(1); _Pragma("unroll") for (int m = 0; m < 4; ++m) _Pragma("unroll") for (int n = 0; n < 2; ++n) _Pragma("unroll") for (int k = 0; k < 2; ++k) \
;         acc[ai][bj][m][n] = __builtin_amdgcn_mfma_f32_16x16x32_bf16(Bt[n][k], At[m][k], acc[ai][bj][m][n], 0, 0, 0); __builtin_amdgcn_s_setprio(0); } while (0)
; #define PG8_WAIT_V(n) asm volatile("s_waitcnt vmcnt(" #n ")" ::: "memory")
; #define PG8_WAIT_L(n) asm volatile("s_waitcnt lgkmcnt(" #n ")" ::: "memory")
; #define PG8_BAR __builtin_amdgcn_s_barrier()
; #define PG8_SCHED __builtin_amdgcn_sched_barrier(0)
; template <class Epi, class Sched, bool ALIGN_EPI = true>
; __device__ __forceinline__ void gemm_phase(LAS unsigned char* lds, const Gemm g, const Sched& S, const Epi& E) {
;     ...
;             PG8_LDA(At, 1, 1); PG8_STAGE(PG8_SB(1, 0), b3, voffB); PG8_STAGE(PG8_SB(1, 1), b3 + hB, voffB); PG8_STAGE(PG8_SA(1, 0), a3, voffA);
;             PG8_WAIT_V(8); PG8_WAIT_L(0); PG8_BAR; PG8_MMA(1, 0, At, B0); PG8_MMA(1, 1, At, B1); PG8_BAR; PG8_SCHED;
;         }
	v_mfma_f32_16x16x32_bf16 v[28:31], v[174:177], v[214:217], v[28:31]
	v_mfma_f32_16x16x32_bf16 v[28:31], v[178:181], v[218:221], v[28:31]
	s_setprio 0
	s_add_i32 s26, s30, s61
	v_lshl_add_u64 v[156:157], v[156:157], 0, s[86:87]
	s_mov_b32 m0, s26
	ds_read_b128 v[182:185], v205 offset:49152
	ds_read_b128 v[186:189], v205 offset:50176
	ds_read_b128 v[190:193], v205 offset:51200
	ds_read_b128 v[194:197], v205 offset:52224
	ds_read_b128 v[206:209], v205 offset:53248
	ds_read_b128 v[210:213], v205 offset:54272
	ds_read_b128 v[214:217], v205 offset:55296
	ds_read_b128 v[218:221], v205 offset:56320
	global_load_lds_dwordx4 v[156:157], off
	s_add_i32 m0, s26, 0x2000
	s_add_u32 s26, s44, 0x80080
	v_lshl_add_u64 v[156:157], v[160:161], 0, s[86:87]
	s_addc_u32 s27, s45, 0
	s_add_i32 s30, s31, s61
	global_load_lds_dwordx4 v[156:157], off
	v_lshl_add_u64 v[156:157], s[26:27], 0, v[166:167]
	s_mov_b32 m0, s30
	s_nop 0
	global_load_lds_dwordx4 v[156:157], off
	v_lshl_add_u64 v[156:157], s[26:27], 0, v[0:1]
	s_add_i32 m0, s30, 0x2000
	s_nop 0
	global_load_lds_dwordx4 v[156:157], off
	v_lshl_add_u64 v[156:157], v[162:163], 0, s[86:87]
	s_mov_b32 m0, s75
	s_nop 0
	global_load_lds_dwordx4 v[156:157], off
	v_lshl_add_u64 v[156:157], v[222:223], 0, s[86:87]
	s_mov_b32 m0, s76
	s_nop 0
	global_load_lds_dwordx4 v[156:157], off
	s_waitcnt vmcnt(8)
	s_waitcnt lgkmcnt(0)
	s_barrier
	s_setprio 1
	s_waitcnt lgkmcnt(0)
	v_mfma_f32_16x16x32_bf16 v[60:63], v[132:135], v[182:185], v[60:63]
	v_mfma_f32_16x16x32_bf16 v[60:63], v[136:139], v[186:189], v[60:63]
	v_mfma_f32_16x16x32_bf16 v[68:71], v[140:143], v[182:185], v[68:71]
	v_mfma_f32_16x16x32_bf16 v[68:71], v[144:147], v[186:189], v[68:71]
	v_mfma_f32_16x16x32_bf16 v[40:43], v[132:135], v[190:193], v[40:43]
	v_mfma_f32_16x16x32_bf16 v[40:43], v[136:139], v[194:197], v[40:43]
	v_mfma_f32_16x16x32_bf16 v[64:67], v[140:143], v[190:193], v[64:67]
	v_mfma_f32_16x16x32_bf16 v[64:67], v[144:147], v[194:197], v[64:67]
	v_mfma_f32_16x16x32_bf16 v[24:27], v[132:135], v[206:209], v[24:27]
	v_mfma_f32_16x16x32_bf16 v[24:27], v[136:139], v[210:213], v[24:27]
	v_mfma_f32_16x16x32_bf16 v[56:59], v[140:143], v[206:209], v[56:59]
	v_mfma_f32_16x16x32_bf16 v[56:59], v[144:147], v[210:213], v[56:59]
	v_mfma_f32_16x16x32_bf16 v[12:15], v[132:135], v[214:217], v[12:15]
	v_mfma_f32_16x16x32_bf16 v[12:15], v[136:139], v[218:221], v[12:15]
	v_mfma_f32_16x16x32_bf16 v[48:51], v[140:143], v[214:217], v[48:51]
	v_mfma_f32_16x16x32_bf16 v[48:51], v[144:147], v[218:221], v[48:51]
	s_setprio 0
	s_setprio 1
	v_mfma_f32_16x16x32_bf16 v[104:107], v[148:151], v[182:185], v[104:107]
	v_mfma_f32_16x16x32_bf16 v[104:107], v[152:155], v[186:189], v[104:107]
	v_mfma_f32_16x16x32_bf16 v[20:23], v[174:177], v[182:185], v[20:23]
	v_mfma_f32_16x16x32_bf16 v[20:23], v[178:181], v[186:189], v[20:23]
	v_mfma_f32_16x16x32_bf16 v[92:95], v[148:151], v[190:193], v[92:95]
	v_mfma_f32_16x16x32_bf16 v[92:95], v[152:155], v[194:197], v[92:95]
	v_mfma_f32_16x16x32_bf16 v[16:19], v[174:177], v[190:193], v[16:19]
	v_mfma_f32_16x16x32_bf16 v[16:19], v[178:181], v[194:197], v[16:19]
	v_mfma_f32_16x16x32_bf16 v[76:79], v[148:151], v[206:209], v[76:79]
	v_mfma_f32_16x16x32_bf16 v[76:79], v[152:155], v[210:213], v[76:79]
	v_mfma_f32_16x16x32_bf16 v[8:11], v[174:177], v[206:209], v[8:11]
	v_mfma_f32_16x16x32_bf16 v[8:11], v[178:181], v[210:213], v[8:11]
	v_mfma_f32_16x16x32_bf16 v[52:55], v[148:151], v[214:217], v[52:55]
	v_mfma_f32_16x16x32_bf16 v[52:55], v[152:155], v[218:221], v[52:55]
	s_setprio 2
	s_barrier
	v_mfma_f32_16x16x32_bf16 v[4:7], v[174:177], v[214:217], v[4:7]
	v_mfma_f32_16x16x32_bf16 v[4:7], v[178:181], v[218:221], v[4:7]
	s_setprio 0
	s_add_i32 s25, s25, 2
	s_add_u32 s6, s6, 0x100
	s_addc_u32 s7, s7, 0
	s_add_u32 s19, s19, 0x100
	s_addc_u32 s24, s24, 0
	s_cmp_gt_u32 s25, 29
	s_cbranch_scc1 .Lpeel_exit_828

; #define LAS __attribute__((address_space(3)))
;     __device__ __forceinline__ void operator()(f32x4 (&acc)[2][2][4][2], const Unit& u, int wr, int wc, int fr_, int fq_, int wid, int lane_) const {
;         int lane = lane_; asm volatile("" : "+v"(lane));
;         const int fr = lane & 15, fq = lane >> 4;
;         const int cl = 32 * wc + 8 * fq;
;         LAS float* wl = xbuf + 2048;
;         {
;             const int t = wid * 64 + lane, kind = t >> 6, pr = t & 63, bj = kind >> 2, tap = kind & 3;
;             const float* src = (tap < 3) ? (cw + (size_t)tap * FF2 + bj * FF + u.pn * 128 + 2 * pr) : (cb + bj * FF + u.pn * 128 + 2 * pr);
;             const f32x2 wv = *(const f32x2*)src;
;             if (fr >= 14) {
;                 unsigned xo = (unsigned)(wr * 512 + (fr - 14) * 128 + cl) * 4u; asm volatile("" : "+v"(xo));
;                 LAS unsigned char* xb = (LAS unsigned char*)xbuf + xo;
; #pragma unroll
;                 for (int ai = 0; ai < 2; ++ai)
; #pragma unroll
;                     for (int bj2 = 0; bj2 < 2; ++bj2)
; #pragma unroll
;                         for (int n = 0; n < 2; ++n) *(LAS f32x4*)(xb + (ai * 1024 + bj2 * 256 + 4 * n) * 4) = acc[ai][bj2][3][n];
.LBB0_831:
	s_waitcnt vmcnt(0)
	v_mov_b32_e32 v134, v158
	s_lshl_b32 s44, s82, 7
	v_add_u32_e32 v2, s77, v134
	v_ashrrev_i32_e32 v135, 6, v2
	v_and_b32_e32 v137, 3, v135
	v_lshrrev_b32_e32 v136, 8, v2
	v_mul_u32_u24_e32 v2, 0x2c00, v137
	v_lshlrev_b32_e32 v2, 2, v2
	v_lshl_add_u64 v[132:133], s[2:3], 0, v[2:3]
	v_mov_b32_e32 v2, s9
	v_cmp_eq_u32_e32 vcc, 3, v137
	v_mul_i32_i24_e32 v136, 0x1600, v136
	v_ashrrev_i32_e32 v137, 31, v136
	v_cndmask_b32_e32 v133, v133, v2, vcc
	v_mov_b32_e32 v2, s8
	v_cndmask_b32_e32 v132, v132, v2, vcc
	v_and_b32_e32 v138, 63, v134
	v_lshl_add_u64 v[132:133], v[136:137], 2, v[132:133]
	s_ashr_i32 s45, s44, 31
	v_lshl_add_u64 v[132:133], s[44:45], 2, v[132:133]
	v_lshlrev_b32_e32 v2, 3, v138
	v_lshl_add_u64 v[132:133], v[132:133], 0, v[2:3]
	v_ashrrev_i32_e32 v136, 1, v134
	v_and_b32_e32 v206, 15, v134
	v_and_b32_e32 v136, -8, v136
	v_add_u32_e32 v174, s67, v136
	v_cmp_lt_u32_e32 vcc, 13, v206
	s_and_saveexec_b64 s[6:7], vcc
	s_cbranch_execz .LBB0_833
	v_lshl_add_u32 v136, v206, 7, s78
	v_add_lshl_u32 v136, v136, v174, 2
	s_nop 0
	v_add_u32_e32 v136, 0, v136
	v_add_u32_e32 v136, 0x20000, v136
	ds_write_b128 v136, v[72:75]
	ds_write_b128 v136, v[80:83] offset:16
	ds_write_b128 v136, v[112:115] offset:1024
	ds_write_b128 v136, v[28:31] offset:1040
	ds_write_b128 v136, v[12:15] offset:4096
	ds_write_b128 v136, v[48:51] offset:4112
	ds_write_b128 v136, v[52:55] offset:5120
	ds_write_b128 v136, v[4:7] offset:5136
